# cvt chains: removed redundant per-element lgkmcnt waits after ds_write (5 code copies), on v12
# baseline (speedup 1.0000x reference)
.LBB0_76:
	s_or_b64 exec, exec, s[20:21]
	s_andn2_b64 vcc, exec, s[14:15]
	s_cbranch_vccnz .LBB0_80
	v_ashrrev_i32_e32 v13, 31, v12
	v_lshlrev_b64 v[12:13], 2, v[12:13]
	v_lshl_add_u64 v[14:15], s[6:7], 0, v[12:13]
	global_load_dword v89, v[14:15], off
	s_ashr_i32 s19, s18, 31
	v_lshl_add_u64 v[14:15], s[18:19], 0, v[2:3]
	v_lshl_add_u64 v[12:13], s[12:13], 0, v[12:13]
	v_lshlrev_b64 v[14:15], 2, v[14:15]
	global_load_dword v90, v[12:13], off
	v_lshl_add_u64 v[12:13], s[6:7], 0, v[14:15]
	v_lshl_add_u64 v[14:15], s[12:13], 0, v[14:15]
	global_load_dword v160, v[12:13], off offset:8
	global_load_dword v161, v[14:15], off offset:8
	global_load_dword v162, v[12:13], off offset:16
	global_load_dword v163, v[14:15], off offset:16
	global_load_dword v164, v[12:13], off offset:24
	global_load_dword v165, v[14:15], off offset:24
	global_load_dword v166, v[12:13], off offset:32
	global_load_dword v167, v[14:15], off offset:32
	global_load_dword v168, v[12:13], off offset:40
	global_load_dword v169, v[14:15], off offset:40
	global_load_dword v170, v[12:13], off offset:48
	global_load_dword v171, v[14:15], off offset:48
	global_load_dword v172, v[12:13], off offset:56
	global_load_dword v173, v[14:15], off offset:56
	global_load_dword v174, v[12:13], off offset:64
	global_load_dword v175, v[14:15], off offset:64
	global_load_dword v176, v[12:13], off offset:72
	global_load_dword v177, v[14:15], off offset:72
	global_load_dword v178, v[12:13], off offset:80
	global_load_dword v179, v[14:15], off offset:80
	global_load_dword v180, v[12:13], off offset:88
	global_load_dword v181, v[14:15], off offset:88
	global_load_dword v182, v[12:13], off offset:96
	global_load_dword v183, v[14:15], off offset:96
	global_load_dword v184, v[12:13], off offset:104
	global_load_dword v185, v[14:15], off offset:104
	global_load_dword v186, v[12:13], off offset:112
	global_load_dword v187, v[14:15], off offset:112
	global_load_dword v188, v[12:13], off offset:120
	global_load_dword v189, v[14:15], off offset:120
	global_load_dword v190, v[12:13], off offset:128
	global_load_dword v191, v[14:15], off offset:128
	global_load_dword v192, v[12:13], off offset:136
	global_load_dword v193, v[14:15], off offset:136
	global_load_dword v194, v[12:13], off offset:144
	global_load_dword v195, v[14:15], off offset:144
	global_load_dword v196, v[12:13], off offset:152
	global_load_dword v197, v[14:15], off offset:152
	global_load_dword v198, v[12:13], off offset:160
	global_load_dword v199, v[14:15], off offset:160
	global_load_dword v200, v[12:13], off offset:168
	global_load_dword v201, v[14:15], off offset:168
	global_load_dword v202, v[12:13], off offset:176
	global_load_dword v203, v[14:15], off offset:176
	global_load_dword v204, v[12:13], off offset:184
	global_load_dword v205, v[14:15], off offset:184
	global_load_dword v206, v[12:13], off offset:192
	global_load_dword v207, v[14:15], off offset:192
	global_load_dword v208, v[12:13], off offset:200
	global_load_dword v209, v[14:15], off offset:200
	global_load_dword v210, v[12:13], off offset:208
	global_load_dword v211, v[14:15], off offset:208
	global_load_dword v212, v[12:13], off offset:216
	global_load_dword v213, v[14:15], off offset:216
	global_load_dword v214, v[12:13], off offset:224
	global_load_dword v215, v[14:15], off offset:224
	global_load_dword v216, v[12:13], off offset:232
	global_load_dword v217, v[14:15], off offset:232
	global_load_dword v218, v[12:13], off offset:240
	global_load_dword v219, v[14:15], off offset:240
	global_load_dword v220, v[14:15], off offset:248
	global_load_dword v221, v[12:13], off offset:248
	s_waitcnt vmcnt(0) lgkmcnt(0)
	v_mul_f32_e32 v91, v57, v89
	ds_write_b32 v16, v91
	v_mov_b32_e32 v89, v160
	v_mov_b32_e32 v92, v161
	v_mul_f32_e32 v93, v59, v89
	ds_write_b32 v17, v93
	v_mov_b32_e32 v89, v162
	v_mov_b32_e32 v94, v163
	v_mul_f32_e32 v95, v58, v89
	ds_write_b32 v22, v95
	v_mov_b32_e32 v89, v164
	v_mov_b32_e32 v96, v165
	v_mul_f32_e32 v97, v61, v89
	ds_write_b32 v23, v97
	v_mov_b32_e32 v89, v166
	v_mov_b32_e32 v98, v167
	v_mul_f32_e32 v99, v60, v89
	ds_write_b32 v24, v99
	v_mov_b32_e32 v89, v168
	v_mov_b32_e32 v100, v169
	v_mul_f32_e32 v101, v63, v89
	ds_write_b32 v25, v101
	v_mov_b32_e32 v89, v170
	v_mov_b32_e32 v102, v171
	v_mul_f32_e32 v103, v62, v89
	ds_write_b32 v26, v103
	v_mov_b32_e32 v89, v172
	v_mov_b32_e32 v104, v173
	v_mul_f32_e32 v105, v65, v89
	ds_write_b32 v27, v105
	v_mov_b32_e32 v89, v174
	v_mov_b32_e32 v106, v175
	v_mul_f32_e32 v107, v64, v89
	ds_write_b32 v28, v107
	v_mov_b32_e32 v89, v176
	v_mov_b32_e32 v108, v177
	v_mul_f32_e32 v109, v67, v89
	ds_write_b32 v29, v109
	v_mov_b32_e32 v89, v178
	v_mov_b32_e32 v110, v179
	v_mul_f32_e32 v111, v66, v89
	ds_write_b32 v31, v111
	v_mov_b32_e32 v89, v180
	v_mov_b32_e32 v112, v181
	v_mul_f32_e32 v113, v69, v89
	ds_write_b32 v34, v113
	v_mov_b32_e32 v89, v182
	v_mov_b32_e32 v114, v183
	v_mul_f32_e32 v115, v68, v89
	ds_write_b32 v35, v115
	v_mov_b32_e32 v89, v184
	v_mov_b32_e32 v116, v185
	v_mul_f32_e32 v117, v71, v89
	ds_write_b32 v36, v117
	v_mov_b32_e32 v89, v186
	v_mov_b32_e32 v118, v187
	v_mul_f32_e32 v119, v70, v89
	ds_write_b32 v37, v119
	v_mov_b32_e32 v89, v188
	v_mov_b32_e32 v120, v189
	v_mul_f32_e32 v121, v73, v89
	ds_write_b32 v38, v121
	v_mov_b32_e32 v89, v190
	v_mov_b32_e32 v122, v191
	v_mul_f32_e32 v123, v72, v89
	ds_write_b32 v39, v123
	v_mov_b32_e32 v89, v192
	v_mov_b32_e32 v124, v193
	v_mul_f32_e32 v125, v75, v89
	ds_write_b32 v40, v125
	v_mov_b32_e32 v89, v194
	v_mov_b32_e32 v126, v195
	v_mul_f32_e32 v127, v74, v89
	ds_write_b32 v41, v127
	v_mov_b32_e32 v89, v196
	v_mov_b32_e32 v128, v197
	v_mul_f32_e32 v129, v77, v89
	ds_write_b32 v42, v129
	v_mov_b32_e32 v89, v198
	v_mov_b32_e32 v130, v199
	v_mul_f32_e32 v131, v76, v89
	ds_write_b32 v43, v131
	v_mov_b32_e32 v89, v200
	v_mov_b32_e32 v132, v201
	v_mul_f32_e32 v133, v79, v89
	ds_write_b32 v44, v133
	v_mov_b32_e32 v89, v202
	v_mov_b32_e32 v134, v203
	v_mul_f32_e32 v135, v78, v89
	ds_write_b32 v45, v135
	v_mov_b32_e32 v89, v204
	v_mov_b32_e32 v136, v205
	v_mul_f32_e32 v137, v81, v89
	ds_write_b32 v46, v137
	v_mov_b32_e32 v89, v206
	v_mov_b32_e32 v138, v207
	v_mul_f32_e32 v139, v80, v89
	ds_write_b32 v47, v139
	v_mov_b32_e32 v89, v208
	v_mov_b32_e32 v140, v209
	v_mul_f32_e32 v141, v83, v89
	ds_write_b32 v48, v141
	v_mov_b32_e32 v89, v210
	v_mov_b32_e32 v142, v211
	v_mul_f32_e32 v143, v82, v89
	ds_write_b32 v49, v143
	v_mov_b32_e32 v89, v212
	v_mov_b32_e32 v144, v213
	v_mul_f32_e32 v145, v85, v89
	ds_write_b32 v50, v145
	v_mov_b32_e32 v89, v214
	v_mov_b32_e32 v146, v215
	v_mul_f32_e32 v147, v84, v89
	ds_write_b32 v51, v147
	v_mov_b32_e32 v89, v216
	v_mov_b32_e32 v148, v217
	v_mul_f32_e32 v149, v87, v89
	ds_write_b32 v52, v149
	v_mov_b32_e32 v150, v218
	v_fma_f32 v89, v57, v90, 0
	v_bfe_u32 v90, v91, 16, 1
	v_add3_u32 v90, v91, v90, s30
	v_bfe_u32 v91, v93, 16, 1
	v_and_b32_e32 v90, 0xffff0000, v90
	v_add3_u32 v91, v93, v91, s30
	v_add_f32_e32 v90, 0, v90
	v_and_b32_e32 v91, 0xffff0000, v91
	v_add_f32_e32 v90, v90, v91
	v_bfe_u32 v91, v95, 16, 1
	v_add3_u32 v91, v95, v91, s30
	v_and_b32_e32 v91, 0xffff0000, v91
	v_add_f32_e32 v90, v90, v91
	v_bfe_u32 v91, v97, 16, 1
	v_add3_u32 v91, v97, v91, s30
	v_and_b32_e32 v91, 0xffff0000, v91
	v_add_f32_e32 v90, v90, v91
	v_bfe_u32 v91, v99, 16, 1
	v_add3_u32 v91, v99, v91, s30
	v_and_b32_e32 v91, 0xffff0000, v91
	v_add_f32_e32 v90, v90, v91
	v_bfe_u32 v91, v101, 16, 1
	v_add3_u32 v91, v101, v91, s30
	v_and_b32_e32 v91, 0xffff0000, v91
	v_add_f32_e32 v90, v90, v91
	v_bfe_u32 v91, v103, 16, 1
	v_add3_u32 v91, v103, v91, s30
	v_and_b32_e32 v91, 0xffff0000, v91
	v_add_f32_e32 v90, v90, v91
	v_bfe_u32 v91, v105, 16, 1
	v_add3_u32 v91, v105, v91, s30
	v_and_b32_e32 v91, 0xffff0000, v91
	v_add_f32_e32 v90, v90, v91
	v_bfe_u32 v91, v107, 16, 1
	v_add3_u32 v91, v107, v91, s30
	v_and_b32_e32 v91, 0xffff0000, v91
	v_add_f32_e32 v90, v90, v91
	v_bfe_u32 v91, v109, 16, 1
	v_add3_u32 v91, v109, v91, s30
	v_and_b32_e32 v91, 0xffff0000, v91
	v_add_f32_e32 v90, v90, v91
	v_bfe_u32 v91, v111, 16, 1
	v_add3_u32 v91, v111, v91, s30
	v_and_b32_e32 v91, 0xffff0000, v91
	v_add_f32_e32 v90, v90, v91
	v_bfe_u32 v91, v113, 16, 1
	v_add3_u32 v91, v113, v91, s30
	v_and_b32_e32 v91, 0xffff0000, v91
	v_add_f32_e32 v90, v90, v91
	v_bfe_u32 v91, v115, 16, 1
	v_add3_u32 v91, v115, v91, s30
	v_and_b32_e32 v91, 0xffff0000, v91
	v_add_f32_e32 v90, v90, v91
	v_bfe_u32 v91, v117, 16, 1
	v_add3_u32 v91, v117, v91, s30
	v_and_b32_e32 v91, 0xffff0000, v91
	v_add_f32_e32 v90, v90, v91
	v_bfe_u32 v91, v119, 16, 1
	v_add3_u32 v91, v119, v91, s30
	v_and_b32_e32 v91, 0xffff0000, v91
	v_fmac_f32_e32 v89, v59, v92
	v_add_f32_e32 v90, v90, v91
	v_mov_b32_e32 v91, v219
	v_fmac_f32_e32 v89, v58, v94
	v_bfe_u32 v92, v121, 16, 1
	v_fmac_f32_e32 v89, v61, v96
	v_fmac_f32_e32 v89, v60, v98
	v_fmac_f32_e32 v89, v63, v100
	v_fmac_f32_e32 v89, v62, v102
	v_fmac_f32_e32 v89, v65, v104
	v_fmac_f32_e32 v89, v64, v106
	v_fmac_f32_e32 v89, v67, v108
	v_fmac_f32_e32 v89, v66, v110
	v_fmac_f32_e32 v89, v69, v112
	v_fmac_f32_e32 v89, v68, v114
	v_fmac_f32_e32 v89, v71, v116
	v_fmac_f32_e32 v89, v70, v118
	v_fmac_f32_e32 v89, v73, v120
	v_fmac_f32_e32 v89, v72, v122
	s_waitcnt vmcnt(0) lgkmcnt(0)
	v_mul_f32_e32 v93, v86, v150
	ds_write_b32 v53, v93
	v_mov_b32_e32 v94, v220
	v_mov_b32_e32 v95, v221
	v_add3_u32 v12, v121, v92, s30
	v_bfe_u32 v13, v123, 16, 1
	v_and_b32_e32 v12, 0xffff0000, v12
	v_add3_u32 v13, v123, v13, s30
	v_add_f32_e32 v12, v90, v12
	v_and_b32_e32 v13, 0xffff0000, v13
	v_add_f32_e32 v12, v12, v13
	v_bfe_u32 v13, v125, 16, 1
	v_add3_u32 v13, v125, v13, s30
	v_and_b32_e32 v13, 0xffff0000, v13
	v_add_f32_e32 v12, v12, v13
	v_bfe_u32 v13, v127, 16, 1
	v_add3_u32 v13, v127, v13, s30
	v_and_b32_e32 v13, 0xffff0000, v13
	v_add_f32_e32 v12, v12, v13
	v_bfe_u32 v13, v129, 16, 1
	v_add3_u32 v13, v129, v13, s30
	v_and_b32_e32 v13, 0xffff0000, v13
	v_add_f32_e32 v12, v12, v13
	v_bfe_u32 v13, v131, 16, 1
	v_add3_u32 v13, v131, v13, s30
	v_and_b32_e32 v13, 0xffff0000, v13
	v_add_f32_e32 v12, v12, v13
	v_bfe_u32 v13, v133, 16, 1
	v_add3_u32 v13, v133, v13, s30
	v_and_b32_e32 v13, 0xffff0000, v13
	v_add_f32_e32 v12, v12, v13
	v_bfe_u32 v13, v135, 16, 1
	v_add3_u32 v13, v135, v13, s30
	v_and_b32_e32 v13, 0xffff0000, v13
	v_add_f32_e32 v12, v12, v13
	v_bfe_u32 v13, v137, 16, 1
	v_add3_u32 v13, v137, v13, s30
	v_and_b32_e32 v13, 0xffff0000, v13
	v_add_f32_e32 v12, v12, v13
	v_bfe_u32 v13, v139, 16, 1
	v_add3_u32 v13, v139, v13, s30
	v_and_b32_e32 v13, 0xffff0000, v13
	v_add_f32_e32 v12, v12, v13
	v_bfe_u32 v13, v141, 16, 1
	v_add3_u32 v13, v141, v13, s30
	v_and_b32_e32 v13, 0xffff0000, v13
	v_add_f32_e32 v12, v12, v13
	v_bfe_u32 v13, v143, 16, 1
	v_add3_u32 v13, v143, v13, s30
	v_and_b32_e32 v13, 0xffff0000, v13
	v_add_f32_e32 v12, v12, v13
	v_bfe_u32 v13, v145, 16, 1
	v_fmac_f32_e32 v89, v75, v124
	v_add3_u32 v13, v145, v13, s30
	v_fmac_f32_e32 v89, v74, v126
	v_and_b32_e32 v13, 0xffff0000, v13
	v_fmac_f32_e32 v89, v77, v128
	v_add_f32_e32 v12, v12, v13
	v_bfe_u32 v13, v147, 16, 1
	v_fmac_f32_e32 v89, v76, v130
	v_add3_u32 v13, v147, v13, s30
	v_fmac_f32_e32 v89, v79, v132
	v_and_b32_e32 v13, 0xffff0000, v13
	v_fmac_f32_e32 v89, v78, v134
	v_add_f32_e32 v12, v12, v13
	v_bfe_u32 v13, v149, 16, 1
	v_fmac_f32_e32 v89, v81, v136
	v_add3_u32 v13, v149, v13, s30
	v_fmac_f32_e32 v89, v80, v138
	v_and_b32_e32 v13, 0xffff0000, v13
	v_fmac_f32_e32 v89, v83, v140
	v_add_f32_e32 v12, v12, v13
	v_bfe_u32 v13, v93, 16, 1
	v_fmac_f32_e32 v89, v82, v142
	v_add3_u32 v13, v93, v13, s30
	v_fmac_f32_e32 v89, v85, v144
	v_and_b32_e32 v13, 0xffff0000, v13
	v_fmac_f32_e32 v89, v84, v146
	v_add_f32_e32 v12, v12, v13
	v_fmac_f32_e32 v89, v87, v148
	v_fmac_f32_e32 v89, v86, v91
	s_waitcnt vmcnt(0) lgkmcnt(0)
	v_fmac_f32_e32 v89, v88, v94
	v_mul_f32_e32 v15, v88, v95
	v_bfe_u32 v13, v15, 16, 1
	v_add3_u32 v13, v15, v13, s30
	v_and_b32_e32 v13, 0xffff0000, v13
	v_add_f32_e32 v12, v12, v13
	ds_bpermute_b32 v13, v55, v12
	ds_bpermute_b32 v14, v55, v89
	ds_write_b32 v54, v15
	s_and_saveexec_b64 s[20:21], s[4:5]
	s_cbranch_execz .LBB0_79
	s_waitcnt lgkmcnt(2)
	v_add_f32_e32 v12, v12, v13
	v_mul_f32_e32 v12, 0x4f800000, v12
	s_waitcnt lgkmcnt(1)
	v_add_f32_e32 v89, v89, v14
	v_rndne_f32_e32 v14, v12
	v_mul_f32_e64 v12, |v14|, s31
	v_floor_f32_e32 v12, v12
	v_fma_f32 v13, v12, s38, |v14|
	v_cvt_u32_f32_e32 v90, v13
	v_cvt_u32_f32_e32 v15, v12
	v_ashrrev_i32_e32 v91, 31, v14
	s_ashr_i32 s17, s16, 31
	v_xor_b32_e32 v14, v90, v91
	s_lshl_b64 s[22:23], s[16:17], 3
	v_xor_b32_e32 v15, v15, v91
	v_sub_co_u32_e32 v14, vcc, v14, v91
	v_lshl_add_u64 v[12:13], v[6:7], 0, s[22:23]
	s_nop 0
	v_subb_co_u32_e32 v15, vcc, v15, v91, vcc
	flat_atomic_add_x2 v[12:13], v[14:15]
	v_mul_f32_e32 v12, 0x4f800000, v89
	v_rndne_f32_e32 v14, v12
	v_mul_f32_e64 v12, |v14|, s31
	v_floor_f32_e32 v12, v12
	v_fma_f32 v13, v12, s38, |v14|
	v_cvt_u32_f32_e32 v89, v13
	v_cvt_u32_f32_e32 v15, v12
	v_ashrrev_i32_e32 v90, 31, v14
	v_lshl_add_u64 v[12:13], v[8:9], 0, s[22:23]
	v_xor_b32_e32 v14, v89, v90
	v_xor_b32_e32 v15, v15, v90
	v_sub_co_u32_e32 v14, vcc, v14, v90
	s_nop 1
	v_subb_co_u32_e32 v15, vcc, v15, v90, vcc
	flat_atomic_add_x2 v[12:13], v[14:15]

.LBB0_694:
	s_or_b64 exec, exec, s[16:17]
	v_lshlrev_b32_e32 v184, 2, v74
	global_load_dword v120, v184, s[8:9]
	global_load_dword v121, v184, s[10:11]
	v_lshlrev_b32_e32 v184, 2, v72
	global_load_dword v122, v184, s[8:9]
	global_load_dword v123, v184, s[10:11]
	v_lshlrev_b32_e32 v184, 2, v70
	global_load_dword v124, v184, s[8:9]
	global_load_dword v125, v184, s[10:11]
	v_lshlrev_b32_e32 v184, 2, v68
	global_load_dword v126, v184, s[8:9]
	global_load_dword v127, v184, s[10:11]
	v_lshlrev_b32_e32 v184, 2, v66
	global_load_dword v128, v184, s[8:9]
	global_load_dword v129, v184, s[10:11]
	v_lshlrev_b32_e32 v184, 2, v64
	global_load_dword v130, v184, s[8:9]
	global_load_dword v131, v184, s[10:11]
	v_lshlrev_b32_e32 v184, 2, v62
	global_load_dword v132, v184, s[8:9]
	global_load_dword v133, v184, s[10:11]
	v_lshlrev_b32_e32 v184, 2, v60
	global_load_dword v134, v184, s[8:9]
	global_load_dword v135, v184, s[10:11]
	v_lshlrev_b32_e32 v184, 2, v58
	global_load_dword v136, v184, s[8:9]
	global_load_dword v137, v184, s[10:11]
	v_lshlrev_b32_e32 v184, 2, v56
	global_load_dword v138, v184, s[8:9]
	global_load_dword v139, v184, s[10:11]
	v_lshlrev_b32_e32 v184, 2, v54
	global_load_dword v140, v184, s[8:9]
	global_load_dword v141, v184, s[10:11]
	v_lshlrev_b32_e32 v184, 2, v52
	global_load_dword v142, v184, s[8:9]
	global_load_dword v143, v184, s[10:11]
	v_lshlrev_b32_e32 v184, 2, v50
	global_load_dword v144, v184, s[8:9]
	global_load_dword v145, v184, s[10:11]
	v_lshlrev_b32_e32 v184, 2, v48
	global_load_dword v146, v184, s[8:9]
	global_load_dword v147, v184, s[10:11]
	v_lshlrev_b32_e32 v184, 2, v46
	global_load_dword v148, v184, s[8:9]
	global_load_dword v149, v184, s[10:11]
	v_lshlrev_b32_e32 v184, 2, v44
	global_load_dword v150, v184, s[8:9]
	global_load_dword v151, v184, s[10:11]
	v_lshlrev_b32_e32 v184, 2, v42
	global_load_dword v152, v184, s[8:9]
	global_load_dword v153, v184, s[10:11]
	v_lshlrev_b32_e32 v184, 2, v40
	global_load_dword v154, v184, s[8:9]
	global_load_dword v155, v184, s[10:11]
	v_lshlrev_b32_e32 v184, 2, v38
	global_load_dword v156, v184, s[8:9]
	global_load_dword v157, v184, s[10:11]
	v_lshlrev_b32_e32 v184, 2, v36
	global_load_dword v158, v184, s[8:9]
	global_load_dword v159, v184, s[10:11]
	v_lshlrev_b32_e32 v184, 2, v34
	global_load_dword v160, v184, s[8:9]
	global_load_dword v161, v184, s[10:11]
	v_lshlrev_b32_e32 v184, 2, v32
	global_load_dword v162, v184, s[8:9]
	global_load_dword v163, v184, s[10:11]
	v_lshlrev_b32_e32 v184, 2, v30
	global_load_dword v164, v184, s[8:9]
	global_load_dword v165, v184, s[10:11]
	v_lshlrev_b32_e32 v184, 2, v28
	global_load_dword v166, v184, s[8:9]
	global_load_dword v167, v184, s[10:11]
	v_lshlrev_b32_e32 v184, 2, v26
	global_load_dword v168, v184, s[8:9]
	global_load_dword v169, v184, s[10:11]
	v_lshlrev_b32_e32 v184, 2, v24
	global_load_dword v170, v184, s[8:9]
	global_load_dword v171, v184, s[10:11]
	v_lshlrev_b32_e32 v184, 2, v22
	global_load_dword v172, v184, s[8:9]
	global_load_dword v173, v184, s[10:11]
	v_lshlrev_b32_e32 v184, 2, v20
	global_load_dword v174, v184, s[8:9]
	global_load_dword v175, v184, s[10:11]
	v_lshlrev_b32_e32 v184, 2, v18
	global_load_dword v176, v184, s[8:9]
	global_load_dword v177, v184, s[10:11]
	v_lshlrev_b32_e32 v184, 2, v16
	global_load_dword v178, v184, s[8:9]
	global_load_dword v179, v184, s[10:11]
	v_lshlrev_b32_e32 v184, 2, v14
	global_load_dword v180, v184, s[8:9]
	global_load_dword v181, v184, s[10:11]
	v_lshlrev_b32_e32 v184, 2, v12
	global_load_dword v182, v184, s[8:9]
	global_load_dword v183, v184, s[10:11]
	s_waitcnt vmcnt(0)
	v_ashrrev_i32_e32 v75, 31, v74
	v_lshlrev_b64 v[76:77], 2, v[74:75]
	v_lshl_add_u64 v[74:75], s[10:11], 0, v[76:77]
	v_lshl_add_u64 v[76:77], s[8:9], 0, v[76:77]
	v_mov_b32_e32 v74, v121
	v_lshlrev_b64 v[12:13], 2, v[12:13]
	v_mov_b32_e32 v75, v120
	s_waitcnt vmcnt(0) lgkmcnt(0)
	v_fma_f32 v74, v73, v74, 0
	v_mul_f32_e32 v73, v73, v75
	v_bfe_u32 v75, v73, 16, 1
	v_add3_u32 v75, v73, v75, s34
	ds_write_b32 v3, v73
	v_ashrrev_i32_e32 v73, 31, v72
	v_lshlrev_b64 v[72:73], 2, v[72:73]
	v_lshl_add_u64 v[76:77], s[10:11], 0, v[72:73]
	v_lshl_add_u64 v[72:73], s[8:9], 0, v[72:73]
	v_mov_b32_e32 v76, v123
	v_and_b32_e32 v75, 0xffff0000, v75
	v_mov_b32_e32 v72, v122
	v_add_f32_e32 v75, 0, v75
	s_waitcnt vmcnt(0) lgkmcnt(0)
	v_fmac_f32_e32 v74, v71, v76
	v_mul_f32_e32 v71, v71, v72
	v_bfe_u32 v72, v71, 16, 1
	v_add3_u32 v72, v71, v72, s34
	ds_write_b32 v82, v71
	v_ashrrev_i32_e32 v71, 31, v70
	v_and_b32_e32 v72, 0xffff0000, v72
	v_lshlrev_b64 v[70:71], 2, v[70:71]
	v_add_f32_e32 v75, v75, v72
	v_lshl_add_u64 v[72:73], s[10:11], 0, v[70:71]
	v_lshl_add_u64 v[70:71], s[8:9], 0, v[70:71]
	v_mov_b32_e32 v72, v125
	s_waitcnt vmcnt(0) lgkmcnt(0)
	v_fmac_f32_e32 v74, v69, v72
	v_mov_b32_e32 v70, v124
	v_mul_f32_e32 v69, v69, v70
	v_bfe_u32 v70, v69, 16, 1
	v_add3_u32 v70, v69, v70, s34
	ds_write_b32 v83, v69
	v_ashrrev_i32_e32 v69, 31, v68
	v_and_b32_e32 v70, 0xffff0000, v70
	v_lshlrev_b64 v[68:69], 2, v[68:69]
	v_add_f32_e32 v72, v75, v70
	v_lshl_add_u64 v[70:71], s[10:11], 0, v[68:69]
	v_lshl_add_u64 v[68:69], s[8:9], 0, v[68:69]
	v_mov_b32_e32 v70, v127
	v_fmac_f32_e32 v74, v67, v70
	v_mov_b32_e32 v68, v126
	v_mul_f32_e32 v67, v67, v68
	v_bfe_u32 v68, v67, 16, 1
	v_add3_u32 v68, v67, v68, s34
	ds_write_b32 v84, v67
	v_ashrrev_i32_e32 v67, 31, v66
	v_and_b32_e32 v68, 0xffff0000, v68
	v_lshlrev_b64 v[66:67], 2, v[66:67]
	v_add_f32_e32 v70, v72, v68
	v_lshl_add_u64 v[68:69], s[10:11], 0, v[66:67]
	v_lshl_add_u64 v[66:67], s[8:9], 0, v[66:67]
	v_mov_b32_e32 v68, v129
	v_fmac_f32_e32 v74, v65, v68
	v_mov_b32_e32 v66, v128
	v_mul_f32_e32 v65, v65, v66
	v_bfe_u32 v66, v65, 16, 1
	v_add3_u32 v66, v65, v66, s34
	ds_write_b32 v85, v65
	v_ashrrev_i32_e32 v65, 31, v64
	v_and_b32_e32 v66, 0xffff0000, v66
	v_lshlrev_b64 v[64:65], 2, v[64:65]
	v_add_f32_e32 v68, v70, v66
	v_lshl_add_u64 v[66:67], s[10:11], 0, v[64:65]
	v_lshl_add_u64 v[64:65], s[8:9], 0, v[64:65]
	v_mov_b32_e32 v66, v131
	v_fmac_f32_e32 v74, v63, v66
	v_mov_b32_e32 v64, v130
	v_mul_f32_e32 v63, v63, v64
	v_bfe_u32 v64, v63, 16, 1
	v_add3_u32 v64, v63, v64, s34
	ds_write_b32 v86, v63
	v_ashrrev_i32_e32 v63, 31, v62
	v_and_b32_e32 v64, 0xffff0000, v64
	v_lshlrev_b64 v[62:63], 2, v[62:63]
	v_add_f32_e32 v66, v68, v64
	v_lshl_add_u64 v[64:65], s[10:11], 0, v[62:63]
	v_lshl_add_u64 v[62:63], s[8:9], 0, v[62:63]
	v_mov_b32_e32 v64, v133
	v_fmac_f32_e32 v74, v61, v64
	v_mov_b32_e32 v62, v132
	v_mul_f32_e32 v61, v61, v62
	v_bfe_u32 v62, v61, 16, 1
	v_add3_u32 v62, v61, v62, s34
	ds_write_b32 v87, v61
	v_ashrrev_i32_e32 v61, 31, v60
	v_and_b32_e32 v62, 0xffff0000, v62
	v_lshlrev_b64 v[60:61], 2, v[60:61]
	v_add_f32_e32 v64, v66, v62
	v_lshl_add_u64 v[62:63], s[10:11], 0, v[60:61]
	v_lshl_add_u64 v[60:61], s[8:9], 0, v[60:61]
	v_mov_b32_e32 v62, v135
	v_fmac_f32_e32 v74, v59, v62
	v_mov_b32_e32 v60, v134
	v_mul_f32_e32 v59, v59, v60
	v_bfe_u32 v60, v59, 16, 1
	v_add3_u32 v60, v59, v60, s34
	ds_write_b32 v88, v59
	v_ashrrev_i32_e32 v59, 31, v58
	v_and_b32_e32 v60, 0xffff0000, v60
	v_lshlrev_b64 v[58:59], 2, v[58:59]
	v_add_f32_e32 v62, v64, v60
	v_lshl_add_u64 v[60:61], s[10:11], 0, v[58:59]
	v_lshl_add_u64 v[58:59], s[8:9], 0, v[58:59]
	v_mov_b32_e32 v60, v137
	v_fmac_f32_e32 v74, v57, v60
	v_mov_b32_e32 v58, v136
	v_mul_f32_e32 v57, v57, v58
	v_bfe_u32 v58, v57, 16, 1
	v_add3_u32 v58, v57, v58, s34
	ds_write_b32 v89, v57
	v_ashrrev_i32_e32 v57, 31, v56
	v_and_b32_e32 v58, 0xffff0000, v58
	v_lshlrev_b64 v[56:57], 2, v[56:57]
	v_add_f32_e32 v60, v62, v58
	v_lshl_add_u64 v[58:59], s[10:11], 0, v[56:57]
	v_lshl_add_u64 v[56:57], s[8:9], 0, v[56:57]
	v_mov_b32_e32 v58, v139
	v_fmac_f32_e32 v74, v55, v58
	v_mov_b32_e32 v56, v138
	v_mul_f32_e32 v55, v55, v56
	v_bfe_u32 v56, v55, 16, 1
	v_add3_u32 v56, v55, v56, s34
	ds_write_b32 v90, v55
	v_ashrrev_i32_e32 v55, 31, v54
	v_and_b32_e32 v56, 0xffff0000, v56
	v_lshlrev_b64 v[54:55], 2, v[54:55]
	v_add_f32_e32 v58, v60, v56
	v_lshl_add_u64 v[56:57], s[10:11], 0, v[54:55]
	v_lshl_add_u64 v[54:55], s[8:9], 0, v[54:55]
	v_mov_b32_e32 v56, v141
	v_fmac_f32_e32 v74, v53, v56
	v_mov_b32_e32 v54, v140
	v_mul_f32_e32 v53, v53, v54
	v_bfe_u32 v54, v53, 16, 1
	v_add3_u32 v54, v53, v54, s34
	ds_write_b32 v91, v53
	v_ashrrev_i32_e32 v53, 31, v52
	v_and_b32_e32 v54, 0xffff0000, v54
	v_lshlrev_b64 v[52:53], 2, v[52:53]
	v_add_f32_e32 v56, v58, v54
	v_lshl_add_u64 v[54:55], s[10:11], 0, v[52:53]
	v_lshl_add_u64 v[52:53], s[8:9], 0, v[52:53]
	v_mov_b32_e32 v54, v143
	v_fmac_f32_e32 v74, v51, v54
	v_mov_b32_e32 v52, v142
	v_mul_f32_e32 v51, v51, v52
	v_bfe_u32 v52, v51, 16, 1
	v_add3_u32 v52, v51, v52, s34
	ds_write_b32 v92, v51
	v_ashrrev_i32_e32 v51, 31, v50
	v_and_b32_e32 v52, 0xffff0000, v52
	v_lshlrev_b64 v[50:51], 2, v[50:51]
	v_add_f32_e32 v54, v56, v52
	v_lshl_add_u64 v[52:53], s[10:11], 0, v[50:51]
	v_lshl_add_u64 v[50:51], s[8:9], 0, v[50:51]
	v_mov_b32_e32 v52, v145
	v_fmac_f32_e32 v74, v49, v52
	v_mov_b32_e32 v50, v144
	v_mul_f32_e32 v49, v49, v50
	v_bfe_u32 v50, v49, 16, 1
	v_add3_u32 v50, v49, v50, s34
	ds_write_b32 v93, v49
	v_ashrrev_i32_e32 v49, 31, v48
	v_and_b32_e32 v50, 0xffff0000, v50
	v_lshlrev_b64 v[48:49], 2, v[48:49]
	v_add_f32_e32 v52, v54, v50
	v_lshl_add_u64 v[50:51], s[10:11], 0, v[48:49]
	v_lshl_add_u64 v[48:49], s[8:9], 0, v[48:49]
	v_mov_b32_e32 v50, v147
	v_fmac_f32_e32 v74, v47, v50
	v_mov_b32_e32 v48, v146
	v_mul_f32_e32 v47, v47, v48
	v_bfe_u32 v48, v47, 16, 1
	v_add3_u32 v48, v47, v48, s34
	ds_write_b32 v94, v47
	v_ashrrev_i32_e32 v47, 31, v46
	v_and_b32_e32 v48, 0xffff0000, v48
	v_lshlrev_b64 v[46:47], 2, v[46:47]
	v_add_f32_e32 v50, v52, v48
	v_lshl_add_u64 v[48:49], s[10:11], 0, v[46:47]
	v_lshl_add_u64 v[46:47], s[8:9], 0, v[46:47]
	v_mov_b32_e32 v48, v149
	v_fmac_f32_e32 v74, v45, v48
	v_mov_b32_e32 v46, v148
	v_mul_f32_e32 v45, v45, v46
	v_bfe_u32 v46, v45, 16, 1
	v_add3_u32 v46, v45, v46, s34
	ds_write_b32 v95, v45
	v_ashrrev_i32_e32 v45, 31, v44
	v_and_b32_e32 v46, 0xffff0000, v46
	v_lshlrev_b64 v[44:45], 2, v[44:45]
	v_add_f32_e32 v48, v50, v46
	v_lshl_add_u64 v[46:47], s[10:11], 0, v[44:45]
	v_lshl_add_u64 v[44:45], s[8:9], 0, v[44:45]
	v_mov_b32_e32 v46, v151
	v_fmac_f32_e32 v74, v43, v46
	v_mov_b32_e32 v44, v150
	v_mul_f32_e32 v43, v43, v44
	v_bfe_u32 v44, v43, 16, 1
	v_add3_u32 v44, v43, v44, s34
	ds_write_b32 v96, v43
	v_ashrrev_i32_e32 v43, 31, v42
	v_and_b32_e32 v44, 0xffff0000, v44
	v_lshlrev_b64 v[42:43], 2, v[42:43]
	v_add_f32_e32 v46, v48, v44
	v_lshl_add_u64 v[44:45], s[10:11], 0, v[42:43]
	v_lshl_add_u64 v[42:43], s[8:9], 0, v[42:43]
	v_mov_b32_e32 v44, v153
	v_fmac_f32_e32 v74, v41, v44
	v_mov_b32_e32 v42, v152
	v_mul_f32_e32 v41, v41, v42
	v_bfe_u32 v42, v41, 16, 1
	v_add3_u32 v42, v41, v42, s34
	ds_write_b32 v97, v41
	v_ashrrev_i32_e32 v41, 31, v40
	v_and_b32_e32 v42, 0xffff0000, v42
	v_lshlrev_b64 v[40:41], 2, v[40:41]
	v_add_f32_e32 v44, v46, v42
	v_lshl_add_u64 v[42:43], s[10:11], 0, v[40:41]
	v_lshl_add_u64 v[40:41], s[8:9], 0, v[40:41]
	v_mov_b32_e32 v42, v155
	v_fmac_f32_e32 v74, v39, v42
	v_mov_b32_e32 v40, v154
	v_mul_f32_e32 v39, v39, v40
	v_bfe_u32 v40, v39, 16, 1
	v_add3_u32 v40, v39, v40, s34
	ds_write_b32 v98, v39
	v_ashrrev_i32_e32 v39, 31, v38
	v_and_b32_e32 v40, 0xffff0000, v40
	v_lshlrev_b64 v[38:39], 2, v[38:39]
	v_add_f32_e32 v42, v44, v40
	v_lshl_add_u64 v[40:41], s[10:11], 0, v[38:39]
	v_lshl_add_u64 v[38:39], s[8:9], 0, v[38:39]
	v_mov_b32_e32 v40, v157
	v_fmac_f32_e32 v74, v37, v40
	v_mov_b32_e32 v38, v156
	v_mul_f32_e32 v37, v37, v38
	v_bfe_u32 v38, v37, 16, 1
	v_add3_u32 v38, v37, v38, s34
	ds_write_b32 v99, v37
	v_ashrrev_i32_e32 v37, 31, v36
	v_and_b32_e32 v38, 0xffff0000, v38
	v_lshlrev_b64 v[36:37], 2, v[36:37]
	v_add_f32_e32 v40, v42, v38
	v_lshl_add_u64 v[38:39], s[10:11], 0, v[36:37]
	v_lshl_add_u64 v[36:37], s[8:9], 0, v[36:37]
	v_mov_b32_e32 v38, v159
	v_fmac_f32_e32 v74, v35, v38
	v_mov_b32_e32 v36, v158
	v_mul_f32_e32 v35, v35, v36
	v_bfe_u32 v36, v35, 16, 1
	v_add3_u32 v36, v35, v36, s34
	ds_write_b32 v100, v35
	v_ashrrev_i32_e32 v35, 31, v34
	v_and_b32_e32 v36, 0xffff0000, v36
	v_lshlrev_b64 v[34:35], 2, v[34:35]
	v_add_f32_e32 v38, v40, v36
	v_lshl_add_u64 v[36:37], s[10:11], 0, v[34:35]
	v_lshl_add_u64 v[34:35], s[8:9], 0, v[34:35]
	v_mov_b32_e32 v36, v161
	v_fmac_f32_e32 v74, v33, v36
	v_mov_b32_e32 v34, v160
	v_mul_f32_e32 v33, v33, v34
	v_bfe_u32 v34, v33, 16, 1
	v_add3_u32 v34, v33, v34, s34
	ds_write_b32 v101, v33
	v_ashrrev_i32_e32 v33, 31, v32
	v_and_b32_e32 v34, 0xffff0000, v34
	v_lshlrev_b64 v[32:33], 2, v[32:33]
	v_add_f32_e32 v36, v38, v34
	v_lshl_add_u64 v[34:35], s[10:11], 0, v[32:33]
	v_lshl_add_u64 v[32:33], s[8:9], 0, v[32:33]
	v_mov_b32_e32 v34, v163
	v_fmac_f32_e32 v74, v31, v34
	v_mov_b32_e32 v32, v162
	v_mul_f32_e32 v31, v31, v32
	v_bfe_u32 v32, v31, 16, 1
	v_add3_u32 v32, v31, v32, s34
	ds_write_b32 v102, v31
	v_ashrrev_i32_e32 v31, 31, v30
	v_and_b32_e32 v32, 0xffff0000, v32
	v_lshlrev_b64 v[30:31], 2, v[30:31]
	v_add_f32_e32 v34, v36, v32
	v_lshl_add_u64 v[32:33], s[10:11], 0, v[30:31]
	v_lshl_add_u64 v[30:31], s[8:9], 0, v[30:31]
	v_mov_b32_e32 v32, v165
	v_fmac_f32_e32 v74, v29, v32
	v_mov_b32_e32 v30, v164
	v_mul_f32_e32 v29, v29, v30
	v_bfe_u32 v30, v29, 16, 1
	v_add3_u32 v30, v29, v30, s34
	ds_write_b32 v103, v29
	v_ashrrev_i32_e32 v29, 31, v28
	v_and_b32_e32 v30, 0xffff0000, v30
	v_lshlrev_b64 v[28:29], 2, v[28:29]
	v_add_f32_e32 v32, v34, v30
	v_lshl_add_u64 v[30:31], s[10:11], 0, v[28:29]
	v_lshl_add_u64 v[28:29], s[8:9], 0, v[28:29]
	v_mov_b32_e32 v30, v167
	v_fmac_f32_e32 v74, v27, v30
	v_mov_b32_e32 v28, v166
	v_mul_f32_e32 v27, v27, v28
	v_bfe_u32 v28, v27, 16, 1
	v_add3_u32 v28, v27, v28, s34
	ds_write_b32 v104, v27
	v_ashrrev_i32_e32 v27, 31, v26
	v_and_b32_e32 v28, 0xffff0000, v28
	v_lshlrev_b64 v[26:27], 2, v[26:27]
	v_add_f32_e32 v30, v32, v28
	v_lshl_add_u64 v[28:29], s[10:11], 0, v[26:27]
	v_lshl_add_u64 v[26:27], s[8:9], 0, v[26:27]
	v_mov_b32_e32 v28, v169
	v_fmac_f32_e32 v74, v25, v28
	v_mov_b32_e32 v26, v168
	v_mul_f32_e32 v25, v25, v26
	v_bfe_u32 v26, v25, 16, 1
	v_add3_u32 v26, v25, v26, s34
	ds_write_b32 v105, v25
	v_ashrrev_i32_e32 v25, 31, v24
	v_and_b32_e32 v26, 0xffff0000, v26
	v_lshlrev_b64 v[24:25], 2, v[24:25]
	v_add_f32_e32 v28, v30, v26
	v_lshl_add_u64 v[26:27], s[10:11], 0, v[24:25]
	v_lshl_add_u64 v[24:25], s[8:9], 0, v[24:25]
	v_mov_b32_e32 v26, v171
	v_fmac_f32_e32 v74, v23, v26
	v_mov_b32_e32 v24, v170
	v_mul_f32_e32 v23, v23, v24
	v_bfe_u32 v24, v23, 16, 1
	v_add3_u32 v24, v23, v24, s34
	ds_write_b32 v106, v23
	v_ashrrev_i32_e32 v23, 31, v22
	v_and_b32_e32 v24, 0xffff0000, v24
	v_lshlrev_b64 v[22:23], 2, v[22:23]
	v_add_f32_e32 v26, v28, v24
	v_lshl_add_u64 v[24:25], s[10:11], 0, v[22:23]
	v_lshl_add_u64 v[22:23], s[8:9], 0, v[22:23]
	v_mov_b32_e32 v24, v173
	v_fmac_f32_e32 v74, v21, v24
	v_mov_b32_e32 v22, v172
	v_mul_f32_e32 v21, v21, v22
	v_bfe_u32 v22, v21, 16, 1
	v_add3_u32 v22, v21, v22, s34
	ds_write_b32 v107, v21
	v_ashrrev_i32_e32 v21, 31, v20
	v_and_b32_e32 v22, 0xffff0000, v22
	v_lshlrev_b64 v[20:21], 2, v[20:21]
	v_add_f32_e32 v24, v26, v22
	v_lshl_add_u64 v[22:23], s[10:11], 0, v[20:21]
	v_lshl_add_u64 v[20:21], s[8:9], 0, v[20:21]
	v_mov_b32_e32 v22, v175
	v_fmac_f32_e32 v74, v19, v22
	v_mov_b32_e32 v20, v174
	v_mul_f32_e32 v19, v19, v20
	v_bfe_u32 v20, v19, 16, 1
	v_add3_u32 v20, v19, v20, s34
	ds_write_b32 v108, v19
	v_ashrrev_i32_e32 v19, 31, v18
	v_and_b32_e32 v20, 0xffff0000, v20
	v_lshlrev_b64 v[18:19], 2, v[18:19]
	v_add_f32_e32 v22, v24, v20
	v_lshl_add_u64 v[20:21], s[10:11], 0, v[18:19]
	v_lshl_add_u64 v[18:19], s[8:9], 0, v[18:19]
	v_mov_b32_e32 v20, v177
	v_fmac_f32_e32 v74, v17, v20
	v_mov_b32_e32 v18, v176
	v_mul_f32_e32 v17, v17, v18
	v_bfe_u32 v18, v17, 16, 1
	v_add3_u32 v18, v17, v18, s34
	ds_write_b32 v109, v17
	v_ashrrev_i32_e32 v17, 31, v16
	v_and_b32_e32 v18, 0xffff0000, v18
	v_lshlrev_b64 v[16:17], 2, v[16:17]
	v_add_f32_e32 v20, v22, v18
	v_lshl_add_u64 v[18:19], s[10:11], 0, v[16:17]
	v_lshl_add_u64 v[16:17], s[8:9], 0, v[16:17]
	v_mov_b32_e32 v18, v179
	v_fmac_f32_e32 v74, v15, v18
	v_mov_b32_e32 v16, v178
	v_mul_f32_e32 v15, v15, v16
	v_bfe_u32 v16, v15, 16, 1
	v_add3_u32 v16, v15, v16, s34
	ds_write_b32 v110, v15
	v_ashrrev_i32_e32 v15, 31, v14
	v_and_b32_e32 v16, 0xffff0000, v16
	v_lshlrev_b64 v[14:15], 2, v[14:15]
	v_add_f32_e32 v18, v20, v16
	v_lshl_add_u64 v[16:17], s[10:11], 0, v[14:15]
	v_lshl_add_u64 v[14:15], s[8:9], 0, v[14:15]
	v_mov_b32_e32 v14, v180
	v_mul_f32_e32 v15, v116, v14
	v_mov_b32_e32 v16, v181
	ds_write_b32 v111, v15
	v_bfe_u32 v14, v15, 16, 1
	v_add3_u32 v14, v15, v14, s34
	v_and_b32_e32 v14, 0xffff0000, v14
	v_add_f32_e32 v14, v18, v14
	v_fmac_f32_e32 v74, v116, v16
	v_lshl_add_u64 v[16:17], s[10:11], 0, v[12:13]
	v_lshl_add_u64 v[12:13], s[8:9], 0, v[12:13]
	v_mov_b32_e32 v12, v182
	v_mul_f32_e32 v13, v115, v12
	v_mov_b32_e32 v15, v183
	v_bfe_u32 v12, v13, 16, 1
	v_add3_u32 v12, v13, v12, s34
	v_and_b32_e32 v12, 0xffff0000, v12
	v_add_f32_e32 v12, v14, v12
	ds_write_b32 v112, v13
	ds_bpermute_b32 v13, v113, v12
	s_waitcnt vmcnt(0) lgkmcnt(0)
	v_fmac_f32_e32 v74, v115, v15
	ds_bpermute_b32 v14, v113, v74
	s_and_saveexec_b64 s[16:17], s[0:1]
	s_cbranch_execz .LBB0_622
	v_add_f32_e32 v12, v12, v13
	v_mul_f32_e32 v12, 0x4f800000, v12
	s_waitcnt lgkmcnt(0)
	v_add_f32_e32 v16, v74, v14
	v_rndne_f32_e32 v14, v12
	s_mov_b32 s3, 0x2f800000
	v_mul_f32_e64 v12, |v14|, s3
	v_floor_f32_e32 v12, v12
	s_mov_b32 s15, 0xcf800000
	v_fma_f32 v13, v12, s15, |v14|
	v_cvt_u32_f32_e32 v17, v13
	v_cvt_u32_f32_e32 v15, v12
	v_ashrrev_i32_e32 v18, 31, v14
	s_ashr_i32 s13, s12, 31
	v_xor_b32_e32 v14, v17, v18
	s_lshl_b64 s[12:13], s[12:13], 3
	v_xor_b32_e32 v15, v15, v18
	v_sub_co_u32_e32 v14, vcc, v14, v18
	v_lshl_add_u64 v[12:13], v[6:7], 0, s[12:13]
	s_nop 0
	v_subb_co_u32_e32 v15, vcc, v15, v18, vcc
	flat_atomic_add_x2 v[12:13], v[14:15]
	v_mul_f32_e32 v12, 0x4f800000, v16
	v_rndne_f32_e32 v14, v12
	v_mul_f32_e64 v12, |v14|, s3
	v_floor_f32_e32 v12, v12
	v_fma_f32 v13, v12, s15, |v14|
	v_cvt_u32_f32_e32 v16, v13
	v_cvt_u32_f32_e32 v15, v12
	v_ashrrev_i32_e32 v17, 31, v14
	v_lshl_add_u64 v[12:13], v[8:9], 0, s[12:13]
	v_xor_b32_e32 v14, v16, v17
	v_xor_b32_e32 v15, v15, v17
	v_sub_co_u32_e32 v14, vcc, v14, v17
	s_nop 1
	v_subb_co_u32_e32 v15, vcc, v15, v17, vcc
	flat_atomic_add_x2 v[12:13], v[14:15]
	s_branch .LBB0_622

.LBB0_1026:
	s_or_b64 exec, exec, s[0:1]
	v_lshlrev_b32_e32 v184, 2, v74
	global_load_dword v120, v184, s[6:7]
	global_load_dword v121, v184, s[8:9]
	v_lshlrev_b32_e32 v184, 2, v72
	global_load_dword v122, v184, s[6:7]
	global_load_dword v123, v184, s[8:9]
	v_lshlrev_b32_e32 v184, 2, v70
	global_load_dword v124, v184, s[6:7]
	global_load_dword v125, v184, s[8:9]
	v_lshlrev_b32_e32 v184, 2, v68
	global_load_dword v126, v184, s[6:7]
	global_load_dword v127, v184, s[8:9]
	v_lshlrev_b32_e32 v184, 2, v66
	global_load_dword v128, v184, s[6:7]
	global_load_dword v129, v184, s[8:9]
	v_lshlrev_b32_e32 v184, 2, v64
	global_load_dword v130, v184, s[6:7]
	global_load_dword v131, v184, s[8:9]
	v_lshlrev_b32_e32 v184, 2, v62
	global_load_dword v132, v184, s[6:7]
	global_load_dword v133, v184, s[8:9]
	v_lshlrev_b32_e32 v184, 2, v60
	global_load_dword v134, v184, s[6:7]
	global_load_dword v135, v184, s[8:9]
	v_lshlrev_b32_e32 v184, 2, v58
	global_load_dword v136, v184, s[6:7]
	global_load_dword v137, v184, s[8:9]
	v_lshlrev_b32_e32 v184, 2, v56
	global_load_dword v138, v184, s[6:7]
	global_load_dword v139, v184, s[8:9]
	v_lshlrev_b32_e32 v184, 2, v54
	global_load_dword v140, v184, s[6:7]
	global_load_dword v141, v184, s[8:9]
	v_lshlrev_b32_e32 v184, 2, v52
	global_load_dword v142, v184, s[6:7]
	global_load_dword v143, v184, s[8:9]
	v_lshlrev_b32_e32 v184, 2, v50
	global_load_dword v144, v184, s[6:7]
	global_load_dword v145, v184, s[8:9]
	v_lshlrev_b32_e32 v184, 2, v48
	global_load_dword v146, v184, s[6:7]
	global_load_dword v147, v184, s[8:9]
	v_lshlrev_b32_e32 v184, 2, v46
	global_load_dword v148, v184, s[6:7]
	global_load_dword v149, v184, s[8:9]
	v_lshlrev_b32_e32 v184, 2, v44
	global_load_dword v150, v184, s[6:7]
	global_load_dword v151, v184, s[8:9]
	v_lshlrev_b32_e32 v184, 2, v42
	global_load_dword v152, v184, s[6:7]
	global_load_dword v153, v184, s[8:9]
	v_lshlrev_b32_e32 v184, 2, v40
	global_load_dword v154, v184, s[6:7]
	global_load_dword v155, v184, s[8:9]
	v_lshlrev_b32_e32 v184, 2, v38
	global_load_dword v156, v184, s[6:7]
	global_load_dword v157, v184, s[8:9]
	v_lshlrev_b32_e32 v184, 2, v36
	global_load_dword v158, v184, s[6:7]
	global_load_dword v159, v184, s[8:9]
	v_lshlrev_b32_e32 v184, 2, v34
	global_load_dword v160, v184, s[6:7]
	global_load_dword v161, v184, s[8:9]
	v_lshlrev_b32_e32 v184, 2, v32
	global_load_dword v162, v184, s[6:7]
	global_load_dword v163, v184, s[8:9]
	v_lshlrev_b32_e32 v184, 2, v30
	global_load_dword v164, v184, s[6:7]
	global_load_dword v165, v184, s[8:9]
	v_lshlrev_b32_e32 v184, 2, v28
	global_load_dword v166, v184, s[6:7]
	global_load_dword v167, v184, s[8:9]
	v_lshlrev_b32_e32 v184, 2, v26
	global_load_dword v168, v184, s[6:7]
	global_load_dword v169, v184, s[8:9]
	v_lshlrev_b32_e32 v184, 2, v24
	global_load_dword v170, v184, s[6:7]
	global_load_dword v171, v184, s[8:9]
	v_lshlrev_b32_e32 v184, 2, v22
	global_load_dword v172, v184, s[6:7]
	global_load_dword v173, v184, s[8:9]
	v_lshlrev_b32_e32 v184, 2, v20
	global_load_dword v174, v184, s[6:7]
	global_load_dword v175, v184, s[8:9]
	v_lshlrev_b32_e32 v184, 2, v18
	global_load_dword v176, v184, s[6:7]
	global_load_dword v177, v184, s[8:9]
	v_lshlrev_b32_e32 v184, 2, v16
	global_load_dword v178, v184, s[6:7]
	global_load_dword v179, v184, s[8:9]
	v_lshlrev_b32_e32 v184, 2, v14
	global_load_dword v180, v184, s[6:7]
	global_load_dword v181, v184, s[8:9]
	v_lshlrev_b32_e32 v184, 2, v12
	global_load_dword v182, v184, s[6:7]
	global_load_dword v183, v184, s[8:9]
	s_waitcnt vmcnt(0)
	v_ashrrev_i32_e32 v75, 31, v74
	v_lshlrev_b64 v[76:77], 2, v[74:75]
	v_lshl_add_u64 v[74:75], s[8:9], 0, v[76:77]
	v_lshl_add_u64 v[76:77], s[6:7], 0, v[76:77]
	v_mov_b32_e32 v74, v121
	v_lshlrev_b64 v[12:13], 2, v[12:13]
	v_mov_b32_e32 v75, v120
	s_waitcnt vmcnt(0) lgkmcnt(0)
	v_fma_f32 v74, v73, v74, 0
	v_mul_f32_e32 v73, v73, v75
	v_bfe_u32 v75, v73, 16, 1
	v_add3_u32 v75, v73, v75, s34
	ds_write_b32 v78, v73
	v_ashrrev_i32_e32 v73, 31, v72
	v_lshlrev_b64 v[72:73], 2, v[72:73]
	v_lshl_add_u64 v[76:77], s[8:9], 0, v[72:73]
	v_lshl_add_u64 v[72:73], s[6:7], 0, v[72:73]
	v_mov_b32_e32 v76, v123
	v_and_b32_e32 v75, 0xffff0000, v75
	v_mov_b32_e32 v72, v122
	v_add_f32_e32 v75, 0, v75
	s_waitcnt vmcnt(0) lgkmcnt(0)
	v_fmac_f32_e32 v74, v71, v76
	v_mul_f32_e32 v71, v71, v72
	v_bfe_u32 v72, v71, 16, 1
	v_add3_u32 v72, v71, v72, s34
	ds_write_b32 v79, v71
	v_ashrrev_i32_e32 v71, 31, v70
	v_and_b32_e32 v72, 0xffff0000, v72
	v_lshlrev_b64 v[70:71], 2, v[70:71]
	v_add_f32_e32 v75, v75, v72
	v_lshl_add_u64 v[72:73], s[8:9], 0, v[70:71]
	v_lshl_add_u64 v[70:71], s[6:7], 0, v[70:71]
	v_mov_b32_e32 v72, v125
	s_waitcnt vmcnt(0) lgkmcnt(0)
	v_fmac_f32_e32 v74, v69, v72
	v_mov_b32_e32 v70, v124
	v_mul_f32_e32 v69, v69, v70
	v_bfe_u32 v70, v69, 16, 1
	v_add3_u32 v70, v69, v70, s34
	ds_write_b32 v80, v69
	v_ashrrev_i32_e32 v69, 31, v68
	v_and_b32_e32 v70, 0xffff0000, v70
	v_lshlrev_b64 v[68:69], 2, v[68:69]
	v_add_f32_e32 v72, v75, v70
	v_lshl_add_u64 v[70:71], s[8:9], 0, v[68:69]
	v_lshl_add_u64 v[68:69], s[6:7], 0, v[68:69]
	v_mov_b32_e32 v70, v127
	v_fmac_f32_e32 v74, v67, v70
	v_mov_b32_e32 v68, v126
	v_mul_f32_e32 v67, v67, v68
	v_bfe_u32 v68, v67, 16, 1
	v_add3_u32 v68, v67, v68, s34
	ds_write_b32 v81, v67
	v_ashrrev_i32_e32 v67, 31, v66
	v_and_b32_e32 v68, 0xffff0000, v68
	v_lshlrev_b64 v[66:67], 2, v[66:67]
	v_add_f32_e32 v70, v72, v68
	v_lshl_add_u64 v[68:69], s[8:9], 0, v[66:67]
	v_lshl_add_u64 v[66:67], s[6:7], 0, v[66:67]
	v_mov_b32_e32 v68, v129
	v_fmac_f32_e32 v74, v65, v68
	v_mov_b32_e32 v66, v128
	v_mul_f32_e32 v65, v65, v66
	v_bfe_u32 v66, v65, 16, 1
	v_add3_u32 v66, v65, v66, s34
	ds_write_b32 v82, v65
	v_ashrrev_i32_e32 v65, 31, v64
	v_and_b32_e32 v66, 0xffff0000, v66
	v_lshlrev_b64 v[64:65], 2, v[64:65]
	v_add_f32_e32 v68, v70, v66
	v_lshl_add_u64 v[66:67], s[8:9], 0, v[64:65]
	v_lshl_add_u64 v[64:65], s[6:7], 0, v[64:65]
	v_mov_b32_e32 v66, v131
	v_fmac_f32_e32 v74, v63, v66
	v_mov_b32_e32 v64, v130
	v_mul_f32_e32 v63, v63, v64
	v_bfe_u32 v64, v63, 16, 1
	v_add3_u32 v64, v63, v64, s34
	ds_write_b32 v83, v63
	v_ashrrev_i32_e32 v63, 31, v62
	v_and_b32_e32 v64, 0xffff0000, v64
	v_lshlrev_b64 v[62:63], 2, v[62:63]
	v_add_f32_e32 v66, v68, v64
	v_lshl_add_u64 v[64:65], s[8:9], 0, v[62:63]
	v_lshl_add_u64 v[62:63], s[6:7], 0, v[62:63]
	v_mov_b32_e32 v64, v133
	v_fmac_f32_e32 v74, v61, v64
	v_mov_b32_e32 v62, v132
	v_mul_f32_e32 v61, v61, v62
	v_bfe_u32 v62, v61, 16, 1
	v_add3_u32 v62, v61, v62, s34
	ds_write_b32 v84, v61
	v_ashrrev_i32_e32 v61, 31, v60
	v_and_b32_e32 v62, 0xffff0000, v62
	v_lshlrev_b64 v[60:61], 2, v[60:61]
	v_add_f32_e32 v64, v66, v62
	v_lshl_add_u64 v[62:63], s[8:9], 0, v[60:61]
	v_lshl_add_u64 v[60:61], s[6:7], 0, v[60:61]
	v_mov_b32_e32 v62, v135
	v_fmac_f32_e32 v74, v59, v62
	v_mov_b32_e32 v60, v134
	v_mul_f32_e32 v59, v59, v60
	v_bfe_u32 v60, v59, 16, 1
	v_add3_u32 v60, v59, v60, s34
	ds_write_b32 v85, v59
	v_ashrrev_i32_e32 v59, 31, v58
	v_and_b32_e32 v60, 0xffff0000, v60
	v_lshlrev_b64 v[58:59], 2, v[58:59]
	v_add_f32_e32 v62, v64, v60
	v_lshl_add_u64 v[60:61], s[8:9], 0, v[58:59]
	v_lshl_add_u64 v[58:59], s[6:7], 0, v[58:59]
	v_mov_b32_e32 v60, v137
	v_fmac_f32_e32 v74, v57, v60
	v_mov_b32_e32 v58, v136
	v_mul_f32_e32 v57, v57, v58
	v_bfe_u32 v58, v57, 16, 1
	v_add3_u32 v58, v57, v58, s34
	ds_write_b32 v86, v57
	v_ashrrev_i32_e32 v57, 31, v56
	v_and_b32_e32 v58, 0xffff0000, v58
	v_lshlrev_b64 v[56:57], 2, v[56:57]
	v_add_f32_e32 v60, v62, v58
	v_lshl_add_u64 v[58:59], s[8:9], 0, v[56:57]
	v_lshl_add_u64 v[56:57], s[6:7], 0, v[56:57]
	v_mov_b32_e32 v58, v139
	v_fmac_f32_e32 v74, v55, v58
	v_mov_b32_e32 v56, v138
	v_mul_f32_e32 v55, v55, v56
	v_bfe_u32 v56, v55, 16, 1
	v_add3_u32 v56, v55, v56, s34
	ds_write_b32 v87, v55
	v_ashrrev_i32_e32 v55, 31, v54
	v_and_b32_e32 v56, 0xffff0000, v56
	v_lshlrev_b64 v[54:55], 2, v[54:55]
	v_add_f32_e32 v58, v60, v56
	v_lshl_add_u64 v[56:57], s[8:9], 0, v[54:55]
	v_lshl_add_u64 v[54:55], s[6:7], 0, v[54:55]
	v_mov_b32_e32 v56, v141
	v_fmac_f32_e32 v74, v53, v56
	v_mov_b32_e32 v54, v140
	v_mul_f32_e32 v53, v53, v54
	v_bfe_u32 v54, v53, 16, 1
	v_add3_u32 v54, v53, v54, s34
	ds_write_b32 v88, v53
	v_ashrrev_i32_e32 v53, 31, v52
	v_and_b32_e32 v54, 0xffff0000, v54
	v_lshlrev_b64 v[52:53], 2, v[52:53]
	v_add_f32_e32 v56, v58, v54
	v_lshl_add_u64 v[54:55], s[8:9], 0, v[52:53]
	v_lshl_add_u64 v[52:53], s[6:7], 0, v[52:53]
	v_mov_b32_e32 v54, v143
	v_fmac_f32_e32 v74, v51, v54
	v_mov_b32_e32 v52, v142
	v_mul_f32_e32 v51, v51, v52
	v_bfe_u32 v52, v51, 16, 1
	v_add3_u32 v52, v51, v52, s34
	ds_write_b32 v89, v51
	v_ashrrev_i32_e32 v51, 31, v50
	v_and_b32_e32 v52, 0xffff0000, v52
	v_lshlrev_b64 v[50:51], 2, v[50:51]
	v_add_f32_e32 v54, v56, v52
	v_lshl_add_u64 v[52:53], s[8:9], 0, v[50:51]
	v_lshl_add_u64 v[50:51], s[6:7], 0, v[50:51]
	v_mov_b32_e32 v52, v145
	v_fmac_f32_e32 v74, v49, v52
	v_mov_b32_e32 v50, v144
	v_mul_f32_e32 v49, v49, v50
	v_bfe_u32 v50, v49, 16, 1
	v_add3_u32 v50, v49, v50, s34
	ds_write_b32 v90, v49
	v_ashrrev_i32_e32 v49, 31, v48
	v_and_b32_e32 v50, 0xffff0000, v50
	v_lshlrev_b64 v[48:49], 2, v[48:49]
	v_add_f32_e32 v52, v54, v50
	v_lshl_add_u64 v[50:51], s[8:9], 0, v[48:49]
	v_lshl_add_u64 v[48:49], s[6:7], 0, v[48:49]
	v_mov_b32_e32 v50, v147
	v_fmac_f32_e32 v74, v47, v50
	v_mov_b32_e32 v48, v146
	v_mul_f32_e32 v47, v47, v48
	v_bfe_u32 v48, v47, 16, 1
	v_add3_u32 v48, v47, v48, s34
	ds_write_b32 v91, v47
	v_ashrrev_i32_e32 v47, 31, v46
	v_and_b32_e32 v48, 0xffff0000, v48
	v_lshlrev_b64 v[46:47], 2, v[46:47]
	v_add_f32_e32 v50, v52, v48
	v_lshl_add_u64 v[48:49], s[8:9], 0, v[46:47]
	v_lshl_add_u64 v[46:47], s[6:7], 0, v[46:47]
	v_mov_b32_e32 v48, v149
	v_fmac_f32_e32 v74, v45, v48
	v_mov_b32_e32 v46, v148
	v_mul_f32_e32 v45, v45, v46
	v_bfe_u32 v46, v45, 16, 1
	v_add3_u32 v46, v45, v46, s34
	ds_write_b32 v92, v45
	v_ashrrev_i32_e32 v45, 31, v44
	v_and_b32_e32 v46, 0xffff0000, v46
	v_lshlrev_b64 v[44:45], 2, v[44:45]
	v_add_f32_e32 v48, v50, v46
	v_lshl_add_u64 v[46:47], s[8:9], 0, v[44:45]
	v_lshl_add_u64 v[44:45], s[6:7], 0, v[44:45]
	v_mov_b32_e32 v46, v151
	v_fmac_f32_e32 v74, v43, v46
	v_mov_b32_e32 v44, v150
	v_mul_f32_e32 v43, v43, v44
	v_bfe_u32 v44, v43, 16, 1
	v_add3_u32 v44, v43, v44, s34
	ds_write_b32 v93, v43
	v_ashrrev_i32_e32 v43, 31, v42
	v_and_b32_e32 v44, 0xffff0000, v44
	v_lshlrev_b64 v[42:43], 2, v[42:43]
	v_add_f32_e32 v46, v48, v44
	v_lshl_add_u64 v[44:45], s[8:9], 0, v[42:43]
	v_lshl_add_u64 v[42:43], s[6:7], 0, v[42:43]
	v_mov_b32_e32 v44, v153
	v_fmac_f32_e32 v74, v41, v44
	v_mov_b32_e32 v42, v152
	v_mul_f32_e32 v41, v41, v42
	v_bfe_u32 v42, v41, 16, 1
	v_add3_u32 v42, v41, v42, s34
	ds_write_b32 v94, v41
	v_ashrrev_i32_e32 v41, 31, v40
	v_and_b32_e32 v42, 0xffff0000, v42
	v_lshlrev_b64 v[40:41], 2, v[40:41]
	v_add_f32_e32 v44, v46, v42
	v_lshl_add_u64 v[42:43], s[8:9], 0, v[40:41]
	v_lshl_add_u64 v[40:41], s[6:7], 0, v[40:41]
	v_mov_b32_e32 v42, v155
	v_fmac_f32_e32 v74, v39, v42
	v_mov_b32_e32 v40, v154
	v_mul_f32_e32 v39, v39, v40
	v_bfe_u32 v40, v39, 16, 1
	v_add3_u32 v40, v39, v40, s34
	ds_write_b32 v95, v39
	v_ashrrev_i32_e32 v39, 31, v38
	v_and_b32_e32 v40, 0xffff0000, v40
	v_lshlrev_b64 v[38:39], 2, v[38:39]
	v_add_f32_e32 v42, v44, v40
	v_lshl_add_u64 v[40:41], s[8:9], 0, v[38:39]
	v_lshl_add_u64 v[38:39], s[6:7], 0, v[38:39]
	v_mov_b32_e32 v40, v157
	v_fmac_f32_e32 v74, v37, v40
	v_mov_b32_e32 v38, v156
	v_mul_f32_e32 v37, v37, v38
	v_bfe_u32 v38, v37, 16, 1
	v_add3_u32 v38, v37, v38, s34
	ds_write_b32 v96, v37
	v_ashrrev_i32_e32 v37, 31, v36
	v_and_b32_e32 v38, 0xffff0000, v38
	v_lshlrev_b64 v[36:37], 2, v[36:37]
	v_add_f32_e32 v40, v42, v38
	v_lshl_add_u64 v[38:39], s[8:9], 0, v[36:37]
	v_lshl_add_u64 v[36:37], s[6:7], 0, v[36:37]
	v_mov_b32_e32 v38, v159
	v_fmac_f32_e32 v74, v35, v38
	v_mov_b32_e32 v36, v158
	v_mul_f32_e32 v35, v35, v36
	v_bfe_u32 v36, v35, 16, 1
	v_add3_u32 v36, v35, v36, s34
	ds_write_b32 v97, v35
	v_ashrrev_i32_e32 v35, 31, v34
	v_and_b32_e32 v36, 0xffff0000, v36
	v_lshlrev_b64 v[34:35], 2, v[34:35]
	v_add_f32_e32 v38, v40, v36
	v_lshl_add_u64 v[36:37], s[8:9], 0, v[34:35]
	v_lshl_add_u64 v[34:35], s[6:7], 0, v[34:35]
	v_mov_b32_e32 v36, v161
	v_fmac_f32_e32 v74, v33, v36
	v_mov_b32_e32 v34, v160
	v_mul_f32_e32 v33, v33, v34
	v_bfe_u32 v34, v33, 16, 1
	v_add3_u32 v34, v33, v34, s34
	ds_write_b32 v98, v33
	v_ashrrev_i32_e32 v33, 31, v32
	v_and_b32_e32 v34, 0xffff0000, v34
	v_lshlrev_b64 v[32:33], 2, v[32:33]
	v_add_f32_e32 v36, v38, v34
	v_lshl_add_u64 v[34:35], s[8:9], 0, v[32:33]
	v_lshl_add_u64 v[32:33], s[6:7], 0, v[32:33]
	v_mov_b32_e32 v34, v163
	v_fmac_f32_e32 v74, v31, v34
	v_mov_b32_e32 v32, v162
	v_mul_f32_e32 v31, v31, v32
	v_bfe_u32 v32, v31, 16, 1
	v_add3_u32 v32, v31, v32, s34
	ds_write_b32 v99, v31
	v_ashrrev_i32_e32 v31, 31, v30
	v_and_b32_e32 v32, 0xffff0000, v32
	v_lshlrev_b64 v[30:31], 2, v[30:31]
	v_add_f32_e32 v34, v36, v32
	v_lshl_add_u64 v[32:33], s[8:9], 0, v[30:31]
	v_lshl_add_u64 v[30:31], s[6:7], 0, v[30:31]
	v_mov_b32_e32 v32, v165
	v_fmac_f32_e32 v74, v29, v32
	v_mov_b32_e32 v30, v164
	v_mul_f32_e32 v29, v29, v30
	v_bfe_u32 v30, v29, 16, 1
	v_add3_u32 v30, v29, v30, s34
	ds_write_b32 v100, v29
	v_ashrrev_i32_e32 v29, 31, v28
	v_and_b32_e32 v30, 0xffff0000, v30
	v_lshlrev_b64 v[28:29], 2, v[28:29]
	v_add_f32_e32 v32, v34, v30
	v_lshl_add_u64 v[30:31], s[8:9], 0, v[28:29]
	v_lshl_add_u64 v[28:29], s[6:7], 0, v[28:29]
	v_mov_b32_e32 v30, v167
	v_fmac_f32_e32 v74, v27, v30
	v_mov_b32_e32 v28, v166
	v_mul_f32_e32 v27, v27, v28
	v_bfe_u32 v28, v27, 16, 1
	v_add3_u32 v28, v27, v28, s34
	ds_write_b32 v101, v27
	v_ashrrev_i32_e32 v27, 31, v26
	v_and_b32_e32 v28, 0xffff0000, v28
	v_lshlrev_b64 v[26:27], 2, v[26:27]
	v_add_f32_e32 v30, v32, v28
	v_lshl_add_u64 v[28:29], s[8:9], 0, v[26:27]
	v_lshl_add_u64 v[26:27], s[6:7], 0, v[26:27]
	v_mov_b32_e32 v28, v169
	v_fmac_f32_e32 v74, v25, v28
	v_mov_b32_e32 v26, v168
	v_mul_f32_e32 v25, v25, v26
	v_bfe_u32 v26, v25, 16, 1
	v_add3_u32 v26, v25, v26, s34
	ds_write_b32 v102, v25
	v_ashrrev_i32_e32 v25, 31, v24
	v_and_b32_e32 v26, 0xffff0000, v26
	v_lshlrev_b64 v[24:25], 2, v[24:25]
	v_add_f32_e32 v28, v30, v26
	v_lshl_add_u64 v[26:27], s[8:9], 0, v[24:25]
	v_lshl_add_u64 v[24:25], s[6:7], 0, v[24:25]
	v_mov_b32_e32 v26, v171
	v_fmac_f32_e32 v74, v23, v26
	v_mov_b32_e32 v24, v170
	v_mul_f32_e32 v23, v23, v24
	v_bfe_u32 v24, v23, 16, 1
	v_add3_u32 v24, v23, v24, s34
	ds_write_b32 v103, v23
	v_ashrrev_i32_e32 v23, 31, v22
	v_and_b32_e32 v24, 0xffff0000, v24
	v_lshlrev_b64 v[22:23], 2, v[22:23]
	v_add_f32_e32 v26, v28, v24
	v_lshl_add_u64 v[24:25], s[8:9], 0, v[22:23]
	v_lshl_add_u64 v[22:23], s[6:7], 0, v[22:23]
	v_mov_b32_e32 v24, v173
	v_fmac_f32_e32 v74, v21, v24
	v_mov_b32_e32 v22, v172
	v_mul_f32_e32 v21, v21, v22
	v_bfe_u32 v22, v21, 16, 1
	v_add3_u32 v22, v21, v22, s34
	ds_write_b32 v104, v21
	v_ashrrev_i32_e32 v21, 31, v20
	v_and_b32_e32 v22, 0xffff0000, v22
	v_lshlrev_b64 v[20:21], 2, v[20:21]
	v_add_f32_e32 v24, v26, v22
	v_lshl_add_u64 v[22:23], s[8:9], 0, v[20:21]
	v_lshl_add_u64 v[20:21], s[6:7], 0, v[20:21]
	v_mov_b32_e32 v22, v175
	v_fmac_f32_e32 v74, v19, v22
	v_mov_b32_e32 v20, v174
	v_mul_f32_e32 v19, v19, v20
	v_bfe_u32 v20, v19, 16, 1
	v_add3_u32 v20, v19, v20, s34
	ds_write_b32 v105, v19
	v_ashrrev_i32_e32 v19, 31, v18
	v_and_b32_e32 v20, 0xffff0000, v20
	v_lshlrev_b64 v[18:19], 2, v[18:19]
	v_add_f32_e32 v22, v24, v20
	v_lshl_add_u64 v[20:21], s[8:9], 0, v[18:19]
	v_lshl_add_u64 v[18:19], s[6:7], 0, v[18:19]
	v_mov_b32_e32 v20, v177
	v_fmac_f32_e32 v74, v17, v20
	v_mov_b32_e32 v18, v176
	v_mul_f32_e32 v17, v17, v18
	v_bfe_u32 v18, v17, 16, 1
	v_add3_u32 v18, v17, v18, s34
	ds_write_b32 v106, v17
	v_ashrrev_i32_e32 v17, 31, v16
	v_and_b32_e32 v18, 0xffff0000, v18
	v_lshlrev_b64 v[16:17], 2, v[16:17]
	v_add_f32_e32 v20, v22, v18
	v_lshl_add_u64 v[18:19], s[8:9], 0, v[16:17]
	v_lshl_add_u64 v[16:17], s[6:7], 0, v[16:17]
	v_mov_b32_e32 v18, v179
	v_fmac_f32_e32 v74, v15, v18
	v_mov_b32_e32 v16, v178
	v_mul_f32_e32 v15, v15, v16
	v_bfe_u32 v16, v15, 16, 1
	v_add3_u32 v16, v15, v16, s34
	ds_write_b32 v107, v15
	v_ashrrev_i32_e32 v15, 31, v14
	v_and_b32_e32 v16, 0xffff0000, v16
	v_lshlrev_b64 v[14:15], 2, v[14:15]
	v_add_f32_e32 v18, v20, v16
	v_lshl_add_u64 v[16:17], s[8:9], 0, v[14:15]
	v_lshl_add_u64 v[14:15], s[6:7], 0, v[14:15]
	v_mov_b32_e32 v14, v180
	v_mul_f32_e32 v15, v113, v14
	v_mov_b32_e32 v16, v181
	ds_write_b32 v108, v15
	v_bfe_u32 v14, v15, 16, 1
	v_add3_u32 v14, v15, v14, s34
	v_and_b32_e32 v14, 0xffff0000, v14
	v_add_f32_e32 v14, v18, v14
	v_fmac_f32_e32 v74, v113, v16
	v_lshl_add_u64 v[16:17], s[8:9], 0, v[12:13]
	v_lshl_add_u64 v[12:13], s[6:7], 0, v[12:13]
	v_mov_b32_e32 v12, v182
	v_mul_f32_e32 v13, v112, v12
	v_mov_b32_e32 v15, v183
	v_bfe_u32 v12, v13, 16, 1
	v_add3_u32 v12, v13, v12, s34
	v_and_b32_e32 v12, 0xffff0000, v12
	v_add_f32_e32 v12, v14, v12
	ds_write_b32 v109, v13
	ds_bpermute_b32 v13, v110, v12
	s_waitcnt vmcnt(0) lgkmcnt(0)
	v_fmac_f32_e32 v74, v112, v15
	ds_bpermute_b32 v14, v110, v74
	s_and_saveexec_b64 s[14:15], vcc
	s_cbranch_execz .LBB0_959
	v_add_f32_e32 v12, v12, v13
	v_mul_f32_e32 v12, 0x4f800000, v12
	s_waitcnt lgkmcnt(0)
	v_add_f32_e32 v16, v74, v14
	v_rndne_f32_e32 v14, v12
	s_mov_b32 s3, 0x2f800000
	s_ashr_i32 s11, s10, 31
	v_mul_f32_e64 v12, |v14|, s3
	s_lshl_b64 s[20:21], s[10:11], 3
	v_floor_f32_e32 v12, v12
	s_mov_b32 s11, 0xcf800000
	v_fma_f32 v13, v12, s11, |v14|
	v_cvt_u32_f32_e32 v17, v13
	v_cvt_u32_f32_e32 v15, v12
	v_ashrrev_i32_e32 v18, 31, v14
	v_lshl_add_u64 v[12:13], v[6:7], 0, s[20:21]
	v_xor_b32_e32 v14, v17, v18
	v_xor_b32_e32 v15, v15, v18
	v_sub_co_u32_e64 v14, s[0:1], v14, v18
	s_nop 1
	v_subb_co_u32_e64 v15, s[0:1], v15, v18, s[0:1]
	flat_atomic_add_x2 v[12:13], v[14:15]
	v_mul_f32_e32 v12, 0x4f800000, v16
	v_rndne_f32_e32 v14, v12
	v_mul_f32_e64 v12, |v14|, s3
	v_floor_f32_e32 v12, v12
	v_fma_f32 v13, v12, s11, |v14|
	v_cvt_u32_f32_e32 v16, v13
	v_cvt_u32_f32_e32 v15, v12
	v_ashrrev_i32_e32 v17, 31, v14
	v_lshl_add_u64 v[12:13], v[8:9], 0, s[20:21]
	v_xor_b32_e32 v14, v16, v17
	v_xor_b32_e32 v15, v15, v17
	v_sub_co_u32_e64 v14, s[0:1], v14, v17
	s_nop 1
	v_subb_co_u32_e64 v15, s[0:1], v15, v17, s[0:1]
	flat_atomic_add_x2 v[12:13], v[14:15]
	s_branch .LBB0_959

.LBB0_1165:
	s_or_b64 exec, exec, s[14:15]
	s_andn2_b64 vcc, exec, s[10:11]
	s_cbranch_vccnz .LBB0_1169
	v_ashrrev_i32_e32 v17, 31, v16
	v_lshlrev_b64 v[16:17], 2, v[16:17]
	v_lshl_add_u64 v[18:19], s[8:9], 0, v[16:17]
	v_lshl_add_u64 v[16:17], s[6:7], 0, v[16:17]
	global_load_dword v16, v[16:17], off
	s_ashr_i32 s13, s12, 31
	global_load_dword v18, v[18:19], off
	s_waitcnt vmcnt(0) lgkmcnt(0)
	v_mul_f32_e32 v16, v57, v16
	v_bfe_u32 v17, v16, 16, 1
	v_add3_u32 v17, v16, v17, s34
	v_and_b32_e32 v17, 0xffff0000, v17
	v_add_f32_e32 v89, 0, v17
	ds_write_b32 v7, v16
	v_lshl_add_u64 v[16:17], s[12:13], 0, v[4:5]
	v_fma_f32 v88, v57, v18, 0
	v_lshlrev_b64 v[18:19], 2, v[16:17]
	v_lshl_add_u64 v[16:17], s[8:9], 0, v[18:19]
	global_load_dword v90, v[16:17], off offset:8
	v_lshl_add_u64 v[18:19], s[6:7], 0, v[18:19]
	global_load_dword v120, v[18:19], off offset:8
	global_load_dword v121, v[16:17], off offset:16
	global_load_dword v122, v[18:19], off offset:16
	global_load_dword v123, v[16:17], off offset:24
	global_load_dword v124, v[18:19], off offset:24
	global_load_dword v125, v[16:17], off offset:32
	global_load_dword v126, v[18:19], off offset:32
	global_load_dword v127, v[16:17], off offset:40
	global_load_dword v128, v[18:19], off offset:40
	global_load_dword v129, v[16:17], off offset:48
	global_load_dword v130, v[18:19], off offset:48
	global_load_dword v131, v[16:17], off offset:56
	global_load_dword v132, v[18:19], off offset:56
	global_load_dword v133, v[16:17], off offset:64
	global_load_dword v134, v[18:19], off offset:64
	global_load_dword v135, v[16:17], off offset:72
	global_load_dword v136, v[18:19], off offset:72
	global_load_dword v137, v[16:17], off offset:80
	global_load_dword v138, v[18:19], off offset:80
	global_load_dword v139, v[16:17], off offset:88
	global_load_dword v140, v[18:19], off offset:88
	global_load_dword v141, v[16:17], off offset:96
	global_load_dword v142, v[18:19], off offset:96
	global_load_dword v143, v[16:17], off offset:104
	global_load_dword v144, v[18:19], off offset:104
	global_load_dword v145, v[16:17], off offset:112
	global_load_dword v146, v[18:19], off offset:112
	global_load_dword v147, v[16:17], off offset:120
	global_load_dword v148, v[18:19], off offset:120
	global_load_dword v149, v[16:17], off offset:128
	global_load_dword v150, v[18:19], off offset:128
	global_load_dword v151, v[16:17], off offset:136
	global_load_dword v152, v[18:19], off offset:136
	global_load_dword v153, v[16:17], off offset:144
	global_load_dword v154, v[18:19], off offset:144
	global_load_dword v155, v[16:17], off offset:152
	global_load_dword v156, v[18:19], off offset:152
	global_load_dword v157, v[16:17], off offset:160
	global_load_dword v158, v[18:19], off offset:160
	global_load_dword v159, v[16:17], off offset:168
	global_load_dword v160, v[18:19], off offset:168
	global_load_dword v161, v[16:17], off offset:176
	global_load_dword v162, v[18:19], off offset:176
	global_load_dword v163, v[16:17], off offset:184
	global_load_dword v164, v[18:19], off offset:184
	global_load_dword v165, v[16:17], off offset:192
	global_load_dword v166, v[18:19], off offset:192
	global_load_dword v167, v[16:17], off offset:200
	global_load_dword v168, v[18:19], off offset:200
	global_load_dword v169, v[16:17], off offset:208
	global_load_dword v170, v[18:19], off offset:208
	global_load_dword v171, v[16:17], off offset:216
	global_load_dword v172, v[18:19], off offset:216
	global_load_dword v173, v[16:17], off offset:224
	global_load_dword v174, v[18:19], off offset:224
	global_load_dword v175, v[16:17], off offset:232
	global_load_dword v176, v[18:19], off offset:232
	global_load_dword v177, v[16:17], off offset:240
	global_load_dword v178, v[18:19], off offset:240
	s_waitcnt vmcnt(0)
	s_waitcnt vmcnt(0) lgkmcnt(0)
	v_fmac_f32_e32 v88, v56, v90
	v_mov_b32_e32 v90, v120
	v_mul_f32_e32 v90, v56, v90
	v_bfe_u32 v91, v90, 16, 1
	ds_write_b32 v24, v90
	v_add3_u32 v91, v90, v91, s34
	v_mov_b32_e32 v90, v121
	v_and_b32_e32 v91, 0xffff0000, v91
	v_add_f32_e32 v89, v89, v91
	v_fmac_f32_e32 v88, v59, v90
	v_mov_b32_e32 v90, v122
	v_mul_f32_e32 v90, v59, v90
	v_bfe_u32 v91, v90, 16, 1
	ds_write_b32 v25, v90
	v_add3_u32 v91, v90, v91, s34
	v_mov_b32_e32 v90, v123
	v_and_b32_e32 v91, 0xffff0000, v91
	v_add_f32_e32 v89, v89, v91
	v_fmac_f32_e32 v88, v58, v90
	v_mov_b32_e32 v90, v124
	v_mul_f32_e32 v90, v58, v90
	v_bfe_u32 v91, v90, 16, 1
	ds_write_b32 v26, v90
	v_add3_u32 v91, v90, v91, s34
	v_mov_b32_e32 v90, v125
	v_and_b32_e32 v91, 0xffff0000, v91
	v_add_f32_e32 v89, v89, v91
	v_fmac_f32_e32 v88, v61, v90
	v_mov_b32_e32 v90, v126
	v_mul_f32_e32 v90, v61, v90
	v_bfe_u32 v91, v90, 16, 1
	ds_write_b32 v27, v90
	v_add3_u32 v91, v90, v91, s34
	v_mov_b32_e32 v90, v127
	v_and_b32_e32 v91, 0xffff0000, v91
	v_add_f32_e32 v89, v89, v91
	v_fmac_f32_e32 v88, v60, v90
	v_mov_b32_e32 v90, v128
	v_mul_f32_e32 v90, v60, v90
	v_bfe_u32 v91, v90, 16, 1
	ds_write_b32 v28, v90
	v_add3_u32 v91, v90, v91, s34
	v_mov_b32_e32 v90, v129
	v_and_b32_e32 v91, 0xffff0000, v91
	v_add_f32_e32 v89, v89, v91
	v_fmac_f32_e32 v88, v63, v90
	v_mov_b32_e32 v90, v130
	v_mul_f32_e32 v90, v63, v90
	v_bfe_u32 v91, v90, 16, 1
	ds_write_b32 v29, v90
	v_add3_u32 v91, v90, v91, s34
	v_mov_b32_e32 v90, v131
	v_and_b32_e32 v91, 0xffff0000, v91
	v_add_f32_e32 v89, v89, v91
	v_fmac_f32_e32 v88, v62, v90
	v_mov_b32_e32 v90, v132
	v_mul_f32_e32 v90, v62, v90
	v_bfe_u32 v91, v90, 16, 1
	ds_write_b32 v30, v90
	v_add3_u32 v91, v90, v91, s34
	v_mov_b32_e32 v90, v133
	v_and_b32_e32 v91, 0xffff0000, v91
	v_add_f32_e32 v89, v89, v91
	v_fmac_f32_e32 v88, v65, v90
	v_mov_b32_e32 v90, v134
	v_mul_f32_e32 v90, v65, v90
	v_bfe_u32 v91, v90, 16, 1
	ds_write_b32 v31, v90
	v_add3_u32 v91, v90, v91, s34
	v_mov_b32_e32 v90, v135
	v_and_b32_e32 v91, 0xffff0000, v91
	v_add_f32_e32 v89, v89, v91
	v_fmac_f32_e32 v88, v64, v90
	v_mov_b32_e32 v90, v136
	v_mul_f32_e32 v90, v64, v90
	v_bfe_u32 v91, v90, 16, 1
	ds_write_b32 v32, v90
	v_add3_u32 v91, v90, v91, s34
	v_mov_b32_e32 v90, v137
	v_and_b32_e32 v91, 0xffff0000, v91
	v_add_f32_e32 v89, v89, v91
	v_fmac_f32_e32 v88, v67, v90
	v_mov_b32_e32 v90, v138
	v_mul_f32_e32 v90, v67, v90
	v_bfe_u32 v91, v90, 16, 1
	ds_write_b32 v33, v90
	v_add3_u32 v91, v90, v91, s34
	v_mov_b32_e32 v90, v139
	v_and_b32_e32 v91, 0xffff0000, v91
	v_add_f32_e32 v89, v89, v91
	v_fmac_f32_e32 v88, v66, v90
	v_mov_b32_e32 v90, v140
	v_mul_f32_e32 v90, v66, v90
	v_bfe_u32 v91, v90, 16, 1
	ds_write_b32 v34, v90
	v_add3_u32 v91, v90, v91, s34
	v_mov_b32_e32 v90, v141
	v_and_b32_e32 v91, 0xffff0000, v91
	v_add_f32_e32 v89, v89, v91
	v_fmac_f32_e32 v88, v69, v90
	v_mov_b32_e32 v90, v142
	v_mul_f32_e32 v90, v69, v90
	v_bfe_u32 v91, v90, 16, 1
	ds_write_b32 v35, v90
	v_add3_u32 v91, v90, v91, s34
	v_mov_b32_e32 v90, v143
	v_and_b32_e32 v91, 0xffff0000, v91
	v_add_f32_e32 v89, v89, v91
	v_fmac_f32_e32 v88, v68, v90
	v_mov_b32_e32 v90, v144
	v_mul_f32_e32 v90, v68, v90
	v_bfe_u32 v91, v90, 16, 1
	ds_write_b32 v36, v90
	v_add3_u32 v91, v90, v91, s34
	v_mov_b32_e32 v90, v145
	v_and_b32_e32 v91, 0xffff0000, v91
	v_add_f32_e32 v89, v89, v91
	v_fmac_f32_e32 v88, v71, v90
	v_mov_b32_e32 v90, v146
	v_mul_f32_e32 v90, v71, v90
	v_bfe_u32 v91, v90, 16, 1
	ds_write_b32 v37, v90
	v_add3_u32 v91, v90, v91, s34
	v_mov_b32_e32 v90, v147
	v_and_b32_e32 v91, 0xffff0000, v91
	v_add_f32_e32 v89, v89, v91
	v_fmac_f32_e32 v88, v70, v90
	v_mov_b32_e32 v90, v148
	v_mul_f32_e32 v90, v70, v90
	v_bfe_u32 v91, v90, 16, 1
	ds_write_b32 v38, v90
	v_add3_u32 v91, v90, v91, s34
	v_mov_b32_e32 v90, v149
	v_and_b32_e32 v91, 0xffff0000, v91
	v_add_f32_e32 v89, v89, v91
	v_fmac_f32_e32 v88, v73, v90
	v_mov_b32_e32 v90, v150
	v_mul_f32_e32 v90, v73, v90
	v_bfe_u32 v91, v90, 16, 1
	ds_write_b32 v39, v90
	v_add3_u32 v91, v90, v91, s34
	v_mov_b32_e32 v90, v151
	v_and_b32_e32 v91, 0xffff0000, v91
	v_add_f32_e32 v89, v89, v91
	v_fmac_f32_e32 v88, v72, v90
	v_mov_b32_e32 v90, v152
	v_mul_f32_e32 v90, v72, v90
	v_bfe_u32 v91, v90, 16, 1
	ds_write_b32 v40, v90
	v_add3_u32 v91, v90, v91, s34
	v_mov_b32_e32 v90, v153
	v_and_b32_e32 v91, 0xffff0000, v91
	v_add_f32_e32 v89, v89, v91
	v_fmac_f32_e32 v88, v75, v90
	v_mov_b32_e32 v90, v154
	v_mul_f32_e32 v90, v75, v90
	v_bfe_u32 v91, v90, 16, 1
	ds_write_b32 v41, v90
	v_add3_u32 v91, v90, v91, s34
	v_mov_b32_e32 v90, v155
	v_and_b32_e32 v91, 0xffff0000, v91
	v_add_f32_e32 v89, v89, v91
	v_fmac_f32_e32 v88, v74, v90
	v_mov_b32_e32 v90, v156
	v_mul_f32_e32 v90, v74, v90
	v_bfe_u32 v91, v90, 16, 1
	ds_write_b32 v42, v90
	v_add3_u32 v91, v90, v91, s34
	v_mov_b32_e32 v90, v157
	v_and_b32_e32 v91, 0xffff0000, v91
	v_add_f32_e32 v89, v89, v91
	v_fmac_f32_e32 v88, v77, v90
	v_mov_b32_e32 v90, v158
	v_mul_f32_e32 v90, v77, v90
	v_bfe_u32 v91, v90, 16, 1
	ds_write_b32 v43, v90
	v_add3_u32 v91, v90, v91, s34
	v_mov_b32_e32 v90, v159
	v_and_b32_e32 v91, 0xffff0000, v91
	v_add_f32_e32 v89, v89, v91
	v_fmac_f32_e32 v88, v76, v90
	v_mov_b32_e32 v90, v160
	v_mul_f32_e32 v90, v76, v90
	v_bfe_u32 v91, v90, 16, 1
	ds_write_b32 v44, v90
	v_add3_u32 v91, v90, v91, s34
	v_mov_b32_e32 v90, v161
	v_and_b32_e32 v91, 0xffff0000, v91
	v_add_f32_e32 v89, v89, v91
	v_fmac_f32_e32 v88, v79, v90
	v_mov_b32_e32 v90, v162
	v_mul_f32_e32 v90, v79, v90
	v_bfe_u32 v91, v90, 16, 1
	ds_write_b32 v45, v90
	v_add3_u32 v91, v90, v91, s34
	v_mov_b32_e32 v90, v163
	v_and_b32_e32 v91, 0xffff0000, v91
	v_add_f32_e32 v89, v89, v91
	v_fmac_f32_e32 v88, v78, v90
	v_mov_b32_e32 v90, v164
	v_mul_f32_e32 v90, v78, v90
	v_bfe_u32 v91, v90, 16, 1
	ds_write_b32 v46, v90
	v_add3_u32 v91, v90, v91, s34
	v_mov_b32_e32 v90, v165
	v_and_b32_e32 v91, 0xffff0000, v91
	v_add_f32_e32 v89, v89, v91
	v_fmac_f32_e32 v88, v81, v90
	v_mov_b32_e32 v90, v166
	v_mul_f32_e32 v90, v81, v90
	v_bfe_u32 v91, v90, 16, 1
	ds_write_b32 v47, v90
	v_add3_u32 v91, v90, v91, s34
	v_mov_b32_e32 v90, v167
	v_and_b32_e32 v91, 0xffff0000, v91
	v_add_f32_e32 v89, v89, v91
	v_fmac_f32_e32 v88, v80, v90
	v_mov_b32_e32 v90, v168
	v_mul_f32_e32 v90, v80, v90
	v_bfe_u32 v91, v90, 16, 1
	ds_write_b32 v48, v90
	v_add3_u32 v91, v90, v91, s34
	v_mov_b32_e32 v90, v169
	v_and_b32_e32 v91, 0xffff0000, v91
	v_add_f32_e32 v89, v89, v91
	v_fmac_f32_e32 v88, v83, v90
	v_mov_b32_e32 v90, v170
	v_mul_f32_e32 v90, v83, v90
	v_bfe_u32 v91, v90, 16, 1
	ds_write_b32 v49, v90
	v_add3_u32 v91, v90, v91, s34
	v_mov_b32_e32 v90, v171
	v_and_b32_e32 v91, 0xffff0000, v91
	v_add_f32_e32 v89, v89, v91
	v_fmac_f32_e32 v88, v82, v90
	v_mov_b32_e32 v90, v172
	v_mul_f32_e32 v90, v82, v90
	v_bfe_u32 v91, v90, 16, 1
	ds_write_b32 v50, v90
	v_add3_u32 v91, v90, v91, s34
	v_mov_b32_e32 v90, v173
	v_and_b32_e32 v91, 0xffff0000, v91
	v_add_f32_e32 v89, v89, v91
	v_fmac_f32_e32 v88, v85, v90
	v_mov_b32_e32 v90, v174
	v_mul_f32_e32 v90, v85, v90
	v_bfe_u32 v91, v90, 16, 1
	ds_write_b32 v51, v90
	v_add3_u32 v91, v90, v91, s34
	v_mov_b32_e32 v90, v175
	v_and_b32_e32 v91, 0xffff0000, v91
	v_add_f32_e32 v89, v89, v91
	v_fmac_f32_e32 v88, v84, v90
	v_mov_b32_e32 v90, v176
	v_mul_f32_e32 v90, v84, v90
	v_bfe_u32 v91, v90, 16, 1
	ds_write_b32 v52, v90
	v_add3_u32 v91, v90, v91, s34
	v_mov_b32_e32 v90, v177
	v_and_b32_e32 v91, 0xffff0000, v91
	v_add_f32_e32 v89, v89, v91
	v_fmac_f32_e32 v88, v87, v90
	v_mov_b32_e32 v90, v178
	v_mul_f32_e32 v90, v87, v90
	ds_write_b32 v53, v90
	global_load_dword v16, v[16:17], off offset:248
	v_bfe_u32 v91, v90, 16, 1
	v_add3_u32 v91, v90, v91, s34
	v_and_b32_e32 v91, 0xffff0000, v91
	v_add_f32_e32 v89, v89, v91
	s_waitcnt vmcnt(0) lgkmcnt(0)
	v_fmac_f32_e32 v88, v86, v16
	global_load_dword v16, v[18:19], off offset:248
	ds_bpermute_b32 v18, v55, v88
	s_waitcnt vmcnt(0) lgkmcnt(0)
	v_mul_f32_e32 v17, v86, v16
	v_bfe_u32 v16, v17, 16, 1
	v_add3_u32 v16, v17, v16, s34
	v_and_b32_e32 v16, 0xffff0000, v16
	v_add_f32_e32 v16, v89, v16
	ds_write_b32 v54, v17
	ds_bpermute_b32 v17, v55, v16
	s_and_saveexec_b64 s[14:15], s[0:1]
	s_cbranch_execz .LBB0_1168
	s_waitcnt lgkmcnt(0)
	v_add_f32_e32 v16, v16, v17
	v_mul_f32_e32 v16, 0x4f800000, v16
	v_add_f32_e32 v88, v88, v18
	v_rndne_f32_e32 v18, v16
	s_mov_b32 s3, 0x2f800000
	s_ashr_i32 s5, s4, 31
	v_mul_f32_e64 v16, |v18|, s3
	s_lshl_b64 s[16:17], s[4:5], 3
	v_floor_f32_e32 v16, v16
	s_mov_b32 s5, 0xcf800000
	v_fma_f32 v17, v16, s5, |v18|
	v_cvt_u32_f32_e32 v89, v17
	v_cvt_u32_f32_e32 v19, v16
	v_ashrrev_i32_e32 v90, 31, v18
	v_lshl_add_u64 v[16:17], v[10:11], 0, s[16:17]
	v_xor_b32_e32 v18, v89, v90
	v_xor_b32_e32 v19, v19, v90
	v_sub_co_u32_e32 v18, vcc, v18, v90
	s_nop 1
	v_subb_co_u32_e32 v19, vcc, v19, v90, vcc
	flat_atomic_add_x2 v[16:17], v[18:19]
	v_mul_f32_e32 v16, 0x4f800000, v88
	v_rndne_f32_e32 v18, v16
	v_mul_f32_e64 v16, |v18|, s3
	v_floor_f32_e32 v16, v16
	v_fma_f32 v17, v16, s5, |v18|
	v_cvt_u32_f32_e32 v88, v17
	v_cvt_u32_f32_e32 v19, v16
	v_ashrrev_i32_e32 v89, 31, v18
	v_lshl_add_u64 v[16:17], v[12:13], 0, s[16:17]
	v_xor_b32_e32 v18, v88, v89
	v_xor_b32_e32 v19, v19, v89
	v_sub_co_u32_e32 v18, vcc, v18, v89
	s_nop 1
	v_subb_co_u32_e32 v19, vcc, v19, v89, vcc
	flat_atomic_add_x2 v[16:17], v[18:19]

.LBB0_1310:
	v_ashrrev_i32_e32 v15, 31, v14
	v_readlane_b32 s10, v254, 59
	v_lshlrev_b64 v[16:17], 2, v[14:15]
	v_readlane_b32 s11, v254, 60
	s_nop 1
	v_lshl_add_u64 v[14:15], s[10:11], 0, v[16:17]
	v_lshl_add_u64 v[16:17], s[20:21], 0, v[16:17]
	global_load_dword v86, v[16:17], off
	global_load_dword v85, v[14:15], off
	s_waitcnt vmcnt(0) lgkmcnt(0)
	v_mul_f32_e32 v86, v54, v86
	v_bfe_u32 v87, v86, 16, 1
	ds_write_b32 v5, v86
	v_add3_u32 v87, v86, v87, s34
	global_load_dword v120, v[14:15], off offset:8
	global_load_dword v121, v[16:17], off offset:8
	global_load_dword v122, v[14:15], off offset:16
	global_load_dword v123, v[16:17], off offset:16
	global_load_dword v124, v[14:15], off offset:24
	global_load_dword v125, v[16:17], off offset:24
	global_load_dword v126, v[14:15], off offset:32
	global_load_dword v127, v[16:17], off offset:32
	global_load_dword v128, v[14:15], off offset:40
	global_load_dword v129, v[16:17], off offset:40
	global_load_dword v130, v[14:15], off offset:48
	global_load_dword v131, v[16:17], off offset:48
	global_load_dword v132, v[14:15], off offset:56
	global_load_dword v133, v[16:17], off offset:56
	global_load_dword v134, v[14:15], off offset:64
	global_load_dword v135, v[16:17], off offset:64
	global_load_dword v136, v[14:15], off offset:72
	global_load_dword v137, v[16:17], off offset:72
	global_load_dword v138, v[14:15], off offset:80
	global_load_dword v139, v[16:17], off offset:80
	global_load_dword v140, v[14:15], off offset:88
	global_load_dword v141, v[16:17], off offset:88
	global_load_dword v142, v[14:15], off offset:96
	global_load_dword v143, v[16:17], off offset:96
	global_load_dword v144, v[14:15], off offset:104
	global_load_dword v145, v[16:17], off offset:104
	global_load_dword v146, v[14:15], off offset:112
	global_load_dword v147, v[16:17], off offset:112
	global_load_dword v148, v[14:15], off offset:120
	global_load_dword v149, v[16:17], off offset:120
	global_load_dword v150, v[14:15], off offset:128
	global_load_dword v151, v[16:17], off offset:128
	global_load_dword v152, v[14:15], off offset:136
	global_load_dword v153, v[16:17], off offset:136
	global_load_dword v154, v[14:15], off offset:144
	global_load_dword v155, v[16:17], off offset:144
	global_load_dword v156, v[14:15], off offset:152
	global_load_dword v157, v[16:17], off offset:152
	global_load_dword v158, v[14:15], off offset:160
	global_load_dword v159, v[16:17], off offset:160
	global_load_dword v160, v[14:15], off offset:168
	global_load_dword v161, v[16:17], off offset:168
	global_load_dword v162, v[14:15], off offset:176
	global_load_dword v163, v[16:17], off offset:176
	global_load_dword v164, v[14:15], off offset:184
	global_load_dword v165, v[16:17], off offset:184
	global_load_dword v166, v[14:15], off offset:192
	global_load_dword v167, v[16:17], off offset:192
	global_load_dword v168, v[14:15], off offset:200
	global_load_dword v169, v[16:17], off offset:200
	global_load_dword v170, v[14:15], off offset:208
	global_load_dword v171, v[16:17], off offset:208
	global_load_dword v172, v[14:15], off offset:216
	global_load_dword v173, v[16:17], off offset:216
	global_load_dword v174, v[14:15], off offset:224
	global_load_dword v175, v[16:17], off offset:224
	global_load_dword v176, v[14:15], off offset:232
	global_load_dword v177, v[16:17], off offset:232
	global_load_dword v178, v[14:15], off offset:240
	global_load_dword v179, v[16:17], off offset:240
	s_waitcnt vmcnt(0)
	v_mov_b32_e32 v86, v120
	v_fma_f32 v85, v54, v85, 0
	v_and_b32_e32 v87, 0xffff0000, v87
	v_add_f32_e32 v87, 0, v87
	s_waitcnt vmcnt(0) lgkmcnt(0)
	v_fmac_f32_e32 v85, v53, v86
	v_mov_b32_e32 v86, v121
	v_mul_f32_e32 v86, v53, v86
	v_bfe_u32 v88, v86, 16, 1
	ds_write_b32 v7, v86
	v_add3_u32 v88, v86, v88, s34
	v_mov_b32_e32 v86, v122
	v_and_b32_e32 v88, 0xffff0000, v88
	v_add_f32_e32 v87, v87, v88
	v_fmac_f32_e32 v85, v56, v86
	v_mov_b32_e32 v86, v123
	v_mul_f32_e32 v86, v56, v86
	v_bfe_u32 v88, v86, 16, 1
	ds_write_b32 v18, v86
	v_add3_u32 v88, v86, v88, s34
	v_mov_b32_e32 v86, v124
	v_and_b32_e32 v88, 0xffff0000, v88
	v_add_f32_e32 v87, v87, v88
	v_fmac_f32_e32 v85, v55, v86
	v_mov_b32_e32 v86, v125
	v_mul_f32_e32 v86, v55, v86
	v_bfe_u32 v88, v86, 16, 1
	ds_write_b32 v19, v86
	v_add3_u32 v88, v86, v88, s34
	v_mov_b32_e32 v86, v126
	v_and_b32_e32 v88, 0xffff0000, v88
	v_add_f32_e32 v87, v87, v88
	v_fmac_f32_e32 v85, v58, v86
	v_mov_b32_e32 v86, v127
	v_mul_f32_e32 v86, v58, v86
	v_bfe_u32 v88, v86, 16, 1
	ds_write_b32 v24, v86
	v_add3_u32 v88, v86, v88, s34
	v_mov_b32_e32 v86, v128
	v_and_b32_e32 v88, 0xffff0000, v88
	v_add_f32_e32 v87, v87, v88
	v_fmac_f32_e32 v85, v57, v86
	v_mov_b32_e32 v86, v129
	v_mul_f32_e32 v86, v57, v86
	v_bfe_u32 v88, v86, 16, 1
	ds_write_b32 v25, v86
	v_add3_u32 v88, v86, v88, s34
	v_mov_b32_e32 v86, v130
	v_and_b32_e32 v88, 0xffff0000, v88
	v_add_f32_e32 v87, v87, v88
	v_fmac_f32_e32 v85, v60, v86
	v_mov_b32_e32 v86, v131
	v_mul_f32_e32 v86, v60, v86
	v_bfe_u32 v88, v86, 16, 1
	ds_write_b32 v26, v86
	v_add3_u32 v88, v86, v88, s34
	v_mov_b32_e32 v86, v132
	v_and_b32_e32 v88, 0xffff0000, v88
	v_add_f32_e32 v87, v87, v88
	v_fmac_f32_e32 v85, v59, v86
	v_mov_b32_e32 v86, v133
	v_mul_f32_e32 v86, v59, v86
	v_bfe_u32 v88, v86, 16, 1
	ds_write_b32 v27, v86
	v_add3_u32 v88, v86, v88, s34
	v_mov_b32_e32 v86, v134
	v_and_b32_e32 v88, 0xffff0000, v88
	v_add_f32_e32 v87, v87, v88
	v_fmac_f32_e32 v85, v62, v86
	v_mov_b32_e32 v86, v135
	v_mul_f32_e32 v86, v62, v86
	v_bfe_u32 v88, v86, 16, 1
	ds_write_b32 v28, v86
	v_add3_u32 v88, v86, v88, s34
	v_mov_b32_e32 v86, v136
	v_and_b32_e32 v88, 0xffff0000, v88
	v_add_f32_e32 v87, v87, v88
	v_fmac_f32_e32 v85, v61, v86
	v_mov_b32_e32 v86, v137
	v_mul_f32_e32 v86, v61, v86
	v_bfe_u32 v88, v86, 16, 1
	ds_write_b32 v29, v86
	v_add3_u32 v88, v86, v88, s34
	v_mov_b32_e32 v86, v138
	v_and_b32_e32 v88, 0xffff0000, v88
	v_add_f32_e32 v87, v87, v88
	v_fmac_f32_e32 v85, v64, v86
	v_mov_b32_e32 v86, v139
	v_mul_f32_e32 v86, v64, v86
	v_bfe_u32 v88, v86, 16, 1
	ds_write_b32 v30, v86
	v_add3_u32 v88, v86, v88, s34
	v_mov_b32_e32 v86, v140
	v_and_b32_e32 v88, 0xffff0000, v88
	v_add_f32_e32 v87, v87, v88
	v_fmac_f32_e32 v85, v63, v86
	v_mov_b32_e32 v86, v141
	v_mul_f32_e32 v86, v63, v86
	v_bfe_u32 v88, v86, 16, 1
	ds_write_b32 v31, v86
	v_add3_u32 v88, v86, v88, s34
	v_mov_b32_e32 v86, v142
	v_and_b32_e32 v88, 0xffff0000, v88
	v_add_f32_e32 v87, v87, v88
	v_fmac_f32_e32 v85, v66, v86
	v_mov_b32_e32 v86, v143
	v_mul_f32_e32 v86, v66, v86
	v_bfe_u32 v88, v86, 16, 1
	ds_write_b32 v32, v86
	v_add3_u32 v88, v86, v88, s34
	v_mov_b32_e32 v86, v144
	v_and_b32_e32 v88, 0xffff0000, v88
	v_add_f32_e32 v87, v87, v88
	v_fmac_f32_e32 v85, v65, v86
	v_mov_b32_e32 v86, v145
	v_mul_f32_e32 v86, v65, v86
	v_bfe_u32 v88, v86, 16, 1
	ds_write_b32 v33, v86
	v_add3_u32 v88, v86, v88, s34
	v_mov_b32_e32 v86, v146
	v_and_b32_e32 v88, 0xffff0000, v88
	v_add_f32_e32 v87, v87, v88
	v_fmac_f32_e32 v85, v68, v86
	v_mov_b32_e32 v86, v147
	v_mul_f32_e32 v86, v68, v86
	v_bfe_u32 v88, v86, 16, 1
	ds_write_b32 v34, v86
	v_add3_u32 v88, v86, v88, s34
	v_mov_b32_e32 v86, v148
	v_and_b32_e32 v88, 0xffff0000, v88
	v_add_f32_e32 v87, v87, v88
	v_fmac_f32_e32 v85, v67, v86
	v_mov_b32_e32 v86, v149
	v_mul_f32_e32 v86, v67, v86
	v_bfe_u32 v88, v86, 16, 1
	ds_write_b32 v35, v86
	v_add3_u32 v88, v86, v88, s34
	v_mov_b32_e32 v86, v150
	v_and_b32_e32 v88, 0xffff0000, v88
	v_add_f32_e32 v87, v87, v88
	v_fmac_f32_e32 v85, v70, v86
	v_mov_b32_e32 v86, v151
	v_mul_f32_e32 v86, v70, v86
	v_bfe_u32 v88, v86, 16, 1
	ds_write_b32 v36, v86
	v_add3_u32 v88, v86, v88, s34
	v_mov_b32_e32 v86, v152
	v_and_b32_e32 v88, 0xffff0000, v88
	v_add_f32_e32 v87, v87, v88
	v_fmac_f32_e32 v85, v69, v86
	v_mov_b32_e32 v86, v153
	v_mul_f32_e32 v86, v69, v86
	v_bfe_u32 v88, v86, 16, 1
	ds_write_b32 v37, v86
	v_add3_u32 v88, v86, v88, s34
	v_mov_b32_e32 v86, v154
	v_and_b32_e32 v88, 0xffff0000, v88
	v_add_f32_e32 v87, v87, v88
	v_fmac_f32_e32 v85, v72, v86
	v_mov_b32_e32 v86, v155
	v_mul_f32_e32 v86, v72, v86
	v_bfe_u32 v88, v86, 16, 1
	ds_write_b32 v38, v86
	v_add3_u32 v88, v86, v88, s34
	v_mov_b32_e32 v86, v156
	v_and_b32_e32 v88, 0xffff0000, v88
	v_add_f32_e32 v87, v87, v88
	v_fmac_f32_e32 v85, v71, v86
	v_mov_b32_e32 v86, v157
	v_mul_f32_e32 v86, v71, v86
	v_bfe_u32 v88, v86, 16, 1
	ds_write_b32 v39, v86
	v_add3_u32 v88, v86, v88, s34
	v_mov_b32_e32 v86, v158
	v_and_b32_e32 v88, 0xffff0000, v88
	v_add_f32_e32 v87, v87, v88
	v_fmac_f32_e32 v85, v74, v86
	v_mov_b32_e32 v86, v159
	v_mul_f32_e32 v86, v74, v86
	v_bfe_u32 v88, v86, 16, 1
	ds_write_b32 v40, v86
	v_add3_u32 v88, v86, v88, s34
	v_mov_b32_e32 v86, v160
	v_and_b32_e32 v88, 0xffff0000, v88
	v_add_f32_e32 v87, v87, v88
	v_fmac_f32_e32 v85, v73, v86
	v_mov_b32_e32 v86, v161
	v_mul_f32_e32 v86, v73, v86
	v_bfe_u32 v88, v86, 16, 1
	ds_write_b32 v41, v86
	v_add3_u32 v88, v86, v88, s34
	v_mov_b32_e32 v86, v162
	v_and_b32_e32 v88, 0xffff0000, v88
	v_add_f32_e32 v87, v87, v88
	v_fmac_f32_e32 v85, v76, v86
	v_mov_b32_e32 v86, v163
	v_mul_f32_e32 v86, v76, v86
	v_bfe_u32 v88, v86, 16, 1
	ds_write_b32 v42, v86
	v_add3_u32 v88, v86, v88, s34
	v_mov_b32_e32 v86, v164
	v_and_b32_e32 v88, 0xffff0000, v88
	v_add_f32_e32 v87, v87, v88
	v_fmac_f32_e32 v85, v75, v86
	v_mov_b32_e32 v86, v165
	v_mul_f32_e32 v86, v75, v86
	v_bfe_u32 v88, v86, 16, 1
	ds_write_b32 v43, v86
	v_add3_u32 v88, v86, v88, s34
	v_mov_b32_e32 v86, v166
	v_and_b32_e32 v88, 0xffff0000, v88
	v_add_f32_e32 v87, v87, v88
	v_fmac_f32_e32 v85, v78, v86
	v_mov_b32_e32 v86, v167
	v_mul_f32_e32 v86, v78, v86
	v_bfe_u32 v88, v86, 16, 1
	ds_write_b32 v44, v86
	v_add3_u32 v88, v86, v88, s34
	v_mov_b32_e32 v86, v168
	v_and_b32_e32 v88, 0xffff0000, v88
	v_add_f32_e32 v87, v87, v88
	v_fmac_f32_e32 v85, v77, v86
	v_mov_b32_e32 v86, v169
	v_mul_f32_e32 v86, v77, v86
	v_bfe_u32 v88, v86, 16, 1
	ds_write_b32 v45, v86
	v_add3_u32 v88, v86, v88, s34
	v_mov_b32_e32 v86, v170
	v_and_b32_e32 v88, 0xffff0000, v88
	v_add_f32_e32 v87, v87, v88
	v_fmac_f32_e32 v85, v80, v86
	v_mov_b32_e32 v86, v171
	v_mul_f32_e32 v86, v80, v86
	v_bfe_u32 v88, v86, 16, 1
	ds_write_b32 v46, v86
	v_add3_u32 v88, v86, v88, s34
	v_mov_b32_e32 v86, v172
	v_and_b32_e32 v88, 0xffff0000, v88
	v_add_f32_e32 v87, v87, v88
	v_fmac_f32_e32 v85, v79, v86
	v_mov_b32_e32 v86, v173
	v_mul_f32_e32 v86, v79, v86
	v_bfe_u32 v88, v86, 16, 1
	ds_write_b32 v47, v86
	v_add3_u32 v88, v86, v88, s34
	v_mov_b32_e32 v86, v174
	v_and_b32_e32 v88, 0xffff0000, v88
	v_add_f32_e32 v87, v87, v88
	v_fmac_f32_e32 v85, v82, v86
	v_mov_b32_e32 v86, v175
	v_mul_f32_e32 v86, v82, v86
	v_bfe_u32 v88, v86, 16, 1
	ds_write_b32 v48, v86
	v_add3_u32 v88, v86, v88, s34
	v_mov_b32_e32 v86, v176
	v_and_b32_e32 v88, 0xffff0000, v88
	v_add_f32_e32 v87, v87, v88
	v_fmac_f32_e32 v85, v81, v86
	v_mov_b32_e32 v86, v177
	v_mul_f32_e32 v86, v81, v86
	v_bfe_u32 v88, v86, 16, 1
	ds_write_b32 v49, v86
	v_add3_u32 v88, v86, v88, s34
	v_mov_b32_e32 v86, v178
	v_and_b32_e32 v88, 0xffff0000, v88
	v_add_f32_e32 v87, v87, v88
	v_fmac_f32_e32 v85, v84, v86
	v_mov_b32_e32 v86, v179
	v_mul_f32_e32 v86, v84, v86
	ds_write_b32 v50, v86
	global_load_dword v14, v[14:15], off offset:248
	v_bfe_u32 v88, v86, 16, 1
	v_add3_u32 v88, v86, v88, s34
	v_and_b32_e32 v88, 0xffff0000, v88
	v_add_f32_e32 v87, v87, v88
	s_waitcnt vmcnt(0) lgkmcnt(0)
	v_fmac_f32_e32 v85, v83, v14
	global_load_dword v14, v[16:17], off offset:248
	ds_bpermute_b32 v16, v23, v85
	s_waitcnt vmcnt(0) lgkmcnt(0)
	v_mul_f32_e32 v15, v83, v14
	v_bfe_u32 v14, v15, 16, 1
	v_add3_u32 v14, v15, v14, s34
	v_and_b32_e32 v14, 0xffff0000, v14
	v_add_f32_e32 v14, v87, v14
	ds_write_b32 v51, v15
	ds_bpermute_b32 v15, v23, v14
	s_and_saveexec_b64 s[10:11], s[0:1]
	s_cbranch_execz .LBB0_1312
	s_waitcnt lgkmcnt(0)
	v_add_f32_e32 v14, v14, v15
	v_mul_f32_e32 v14, 0x4f800000, v14
	v_add_f32_e32 v85, v85, v16
	v_rndne_f32_e32 v16, v14
	s_mov_b32 s3, 0x2f800000
	v_mul_f32_e64 v14, |v16|, s3
	v_floor_f32_e32 v14, v14
	s_mov_b32 s7, 0xcf800000
	v_fma_f32 v15, v14, s7, |v16|
	v_cvt_u32_f32_e32 v86, v15
	v_cvt_u32_f32_e32 v17, v14
	v_ashrrev_i32_e32 v87, 31, v16
	s_ashr_i32 s9, s8, 31
	v_xor_b32_e32 v16, v86, v87
	s_lshl_b64 s[8:9], s[8:9], 3
	v_xor_b32_e32 v17, v17, v87
	v_sub_co_u32_e32 v16, vcc, v16, v87
	v_lshl_add_u64 v[14:15], v[2:3], 0, s[8:9]
	s_nop 0
	v_subb_co_u32_e32 v17, vcc, v17, v87, vcc
	flat_atomic_add_x2 v[14:15], v[16:17]
	v_mul_f32_e32 v14, 0x4f800000, v85
	v_rndne_f32_e32 v16, v14
	v_mul_f32_e64 v14, |v16|, s3
	v_floor_f32_e32 v14, v14
	v_fma_f32 v15, v14, s7, |v16|
	v_cvt_u32_f32_e32 v85, v15
	v_cvt_u32_f32_e32 v17, v14
	v_ashrrev_i32_e32 v86, 31, v16
	v_lshl_add_u64 v[14:15], v[10:11], 0, s[8:9]
	v_xor_b32_e32 v16, v85, v86
	v_xor_b32_e32 v17, v17, v86
	v_sub_co_u32_e32 v16, vcc, v16, v86
	s_nop 1
	v_subb_co_u32_e32 v17, vcc, v17, v86, vcc
	flat_atomic_add_x2 v[14:15], v[16:17]
